# GEMM K-loops: back edge rotated - loop-advance and next-iteration head scalars executed before the loop-back barrier
# baseline (speedup 1.0000x reference)
; #define PG8_STAGE(bufoff, gbase, voff) do { _Pragma("unroll") for (int _i = 0; _i < 2; ++_i) \
;         __builtin_amdgcn_global_load_lds((const unsigned*)((const char*)(gbase) + (voff)[_i]), (LAS unsigned*)(lds + (bufoff) + ldsw + _i * 8192), 16, 0, 0); } while (0)
; #define PG8_LDA(dst, b, h) do { _Pragma("unroll") for (int m = 0; m < 4; ++m) _Pragma("unroll") for (int k = 0; k < 2; ++k) dst[m][k] = *(const LAS bf16x8*)(lds + PG8_SA(b, h) + aoff + m * 2048 + k * 1024); } while (0)
; #define PG8_LDB(dst, b, h) do { _Pragma("unroll") for (int n = 0; n < 2; ++n) _Pragma("unroll") for (int k = 0; k < 2; ++k) dst[n][k] = *(const LAS bf16x8*)(lds + PG8_SB(b, h) + boff + n * 2048 + k * 1024); } while (0)
; #define PG8_MMA(ai, bj, At, Bt) do { __builtin_amdgcn_s_setprio(1); _Pragma("unroll") for (int m = 0; m < 4; ++m) _Pragma("unroll") for (int n = 0; n < 2; ++n) _Pragma("unroll") for (int k = 0; k < 2; ++k) \
;         acc[ai][bj][m][n] = __builtin_amdgcn_mfma_f32_16x16x32_bf16(Bt[n][k], At[m][k], acc[ai][bj][m][n], 0, 0, 0); __builtin_amdgcn_s_setprio(0); } while (0)
; #define PG8_WAIT_V(n) asm volatile("s_waitcnt vmcnt(" #n ")" ::: "memory")
; #define PG8_WAIT_L(n) asm volatile("s_waitcnt lgkmcnt(" #n ")" ::: "memory")
; #define PG8_BAR __builtin_amdgcn_s_barrier()
; #define PG8_SCHED __builtin_amdgcn_sched_barrier(0)
; template <bool ALIGN_EPI, class Epi, class Sched>
; DEV void gemm_phase(LAS unsigned char* lds, const Gemm g, const Sched& S, const Epi& E) {
;     ...
;             PG8_LDB(B0, 0, 0); PG8_LDB(B1, 0, 1); PG8_SCHED; PG8_LDA(At, 0, 0); PG8_STAGE(PG8_SA(1, 1), a1 + hstepA, voffA);
;             PG8_WAIT_V(8); PG8_WAIT_L(0); PG8_BAR; PG8_MMA(0, 0, At, B0); PG8_MMA(0, 1, At, B1); PG8_BAR; PG8_SCHED;
;             PG8_LDA(At, 0, 1); PG8_STAGE(PG8_SB(0, 0), b2, voffB); PG8_STAGE(PG8_SB(0, 1), b2 + hstep, voffB); PG8_STAGE(PG8_SA(0, 0), a2, voffA);
;             PG8_WAIT_V(8); PG8_WAIT_L(0); PG8_BAR; PG8_MMA(1, 0, At, B0); PG8_MMA(1, 1, At, B1); PG8_BAR; PG8_SCHED;
.Lkr_28:
	ds_read_b128 v[62:65], v82
	ds_read_b128 v[66:69], v82 offset:1024
	ds_read_b128 v[78:81], v82 offset:2048
	ds_read_b128 v[82:85], v82 offset:3072
	ds_read_b128 v[122:125], v158
	ds_read_b128 v[134:137], v158 offset:1024
	ds_read_b128 v[154:157], v158 offset:2048
	ds_read_b128 v[158:161], v158 offset:3072
	v_lshl_add_u64 v[208:209], s[4:5], 0, v[188:189]
	s_add_i32 m0, s12, 0xc000
	ds_read_b128 v[162:165], v230
	ds_read_b128 v[166:169], v230 offset:1024
	ds_read_b128 v[192:195], v230 offset:2048
	ds_read_b128 v[196:199], v230 offset:3072
	ds_read_b128 v[200:203], v230 offset:4096
	ds_read_b128 v[204:207], v230 offset:5120
	ds_read_b128 v[232:235], v230 offset:6144
	ds_read_b128 v[236:239], v230 offset:7168
	global_load_lds_dwordx4 v[208:209], off
	v_lshl_add_u64 v[208:209], s[4:5], 0, v[190:191]
	s_add_i32 m0, s12, 0xe000
	s_nop 0
	global_load_lds_dwordx4 v[208:209], off
	s_waitcnt vmcnt(8)
	s_waitcnt lgkmcnt(0)
	s_barrier
	s_setprio 1
	s_waitcnt lgkmcnt(0)
	v_mfma_f32_16x16x32_bf16 v[130:133], v[62:65], v[162:165], v[130:133]
	v_mfma_f32_16x16x32_bf16 v[118:121], v[78:81], v[162:165], v[118:121]
	v_mfma_f32_16x16x32_bf16 v[110:113], v[62:65], v[192:195], v[110:113]
	v_mfma_f32_16x16x32_bf16 v[102:105], v[78:81], v[192:195], v[102:105]
	v_mfma_f32_16x16x32_bf16 v[94:97], v[62:65], v[200:203], v[94:97]
	v_mfma_f32_16x16x32_bf16 v[86:89], v[78:81], v[200:203], v[86:89]
	v_mfma_f32_16x16x32_bf16 v[70:73], v[62:65], v[232:235], v[70:73]
	v_mfma_f32_16x16x32_bf16 v[54:57], v[78:81], v[232:235], v[54:57]
	v_mfma_f32_16x16x32_bf16 v[130:133], v[66:69], v[166:169], v[130:133]
	v_mfma_f32_16x16x32_bf16 v[118:121], v[82:85], v[166:169], v[118:121]
	v_mfma_f32_16x16x32_bf16 v[110:113], v[66:69], v[196:199], v[110:113]
	v_mfma_f32_16x16x32_bf16 v[102:105], v[82:85], v[196:199], v[102:105]
	v_mfma_f32_16x16x32_bf16 v[94:97], v[66:69], v[204:207], v[94:97]
	v_mfma_f32_16x16x32_bf16 v[86:89], v[82:85], v[204:207], v[86:89]
	v_mfma_f32_16x16x32_bf16 v[70:73], v[66:69], v[236:239], v[70:73]
	v_mfma_f32_16x16x32_bf16 v[54:57], v[82:85], v[236:239], v[54:57]
	s_setprio 0
	s_setprio 1
	v_mfma_f32_16x16x32_bf16 v[150:153], v[122:125], v[162:165], v[150:153]
	v_mfma_f32_16x16x32_bf16 v[146:149], v[154:157], v[162:165], v[146:149]
	v_mfma_f32_16x16x32_bf16 v[142:145], v[122:125], v[192:195], v[142:145]
	v_mfma_f32_16x16x32_bf16 v[138:141], v[154:157], v[192:195], v[138:141]
	v_mfma_f32_16x16x32_bf16 v[126:129], v[122:125], v[200:203], v[126:129]
	v_mfma_f32_16x16x32_bf16 v[114:117], v[154:157], v[200:203], v[114:117]
	v_mfma_f32_16x16x32_bf16 v[106:109], v[122:125], v[232:235], v[106:109]
	v_mfma_f32_16x16x32_bf16 v[98:101], v[154:157], v[232:235], v[98:101]
	v_mfma_f32_16x16x32_bf16 v[150:153], v[134:137], v[166:169], v[150:153]
	v_mfma_f32_16x16x32_bf16 v[146:149], v[158:161], v[166:169], v[146:149]
	v_mfma_f32_16x16x32_bf16 v[142:145], v[134:137], v[196:199], v[142:145]
	v_mfma_f32_16x16x32_bf16 v[138:141], v[158:161], v[196:199], v[138:141]
	v_mfma_f32_16x16x32_bf16 v[126:129], v[134:137], v[204:207], v[126:129]
	v_mfma_f32_16x16x32_bf16 v[114:117], v[158:161], v[204:207], v[114:117]
	v_mfma_f32_16x16x32_bf16 v[106:109], v[134:137], v[236:239], v[106:109]
	v_mfma_f32_16x16x32_bf16 v[98:101], v[158:161], v[236:239], v[98:101]
	s_setprio 0
	s_barrier
	s_add_i32 s4, s24, s8
	v_lshl_add_u64 v[208:209], s[90:91], 0, v[0:1]
	s_mov_b32 m0, s4
	ds_read_b128 v[162:165], v230 offset:16384
	ds_read_b128 v[166:169], v230 offset:17408
	ds_read_b128 v[192:195], v230 offset:18432
	ds_read_b128 v[196:199], v230 offset:19456
	ds_read_b128 v[200:203], v230 offset:20480
	ds_read_b128 v[204:207], v230 offset:21504
	ds_read_b128 v[232:235], v230 offset:22528
	ds_read_b128 v[236:239], v230 offset:23552
	global_load_lds_dwordx4 v[208:209], off
	s_add_i32 m0, s4, 0x2000
	s_add_u32 s4, s90, 0x40000
	v_lshl_add_u64 v[214:215], s[90:91], 0, v[180:181]
	s_addc_u32 s5, s91, 0
	s_add_i32 s24, s25, s8
	global_load_lds_dwordx4 v[214:215], off
	v_lshl_add_u64 v[240:241], s[4:5], 0, v[0:1]
	s_mov_b32 m0, s24
	v_lshl_add_u64 v[242:243], s[92:93], 0, v[182:183]
	global_load_lds_dwordx4 v[240:241], off
	v_lshl_add_u64 v[240:241], s[4:5], 0, v[180:181]
	s_add_i32 m0, s24, 0x2000
	s_nop 0
	global_load_lds_dwordx4 v[240:241], off
	v_lshl_add_u64 v[240:241], s[92:93], 0, v[184:185]
	s_mov_b32 m0, s12
	s_nop 0
	global_load_lds_dwordx4 v[240:241], off
	s_mov_b32 m0, s13
	s_nop 0
	global_load_lds_dwordx4 v[242:243], off
	s_waitcnt vmcnt(8)
	s_waitcnt lgkmcnt(0)
	s_barrier
	s_setprio 1
	s_waitcnt lgkmcnt(0)
	v_mfma_f32_16x16x32_bf16 v[46:49], v[62:65], v[162:165], v[46:49]
	v_mfma_f32_16x16x32_bf16 v[38:41], v[78:81], v[162:165], v[38:41]
	v_mfma_f32_16x16x32_bf16 v[30:33], v[62:65], v[192:195], v[30:33]
	v_mfma_f32_16x16x32_bf16 v[14:17], v[78:81], v[192:195], v[14:17]
	v_mfma_f32_16x16x32_bf16 v[26:29], v[62:65], v[200:203], v[26:29]
	v_mfma_f32_16x16x32_bf16 v[10:13], v[78:81], v[200:203], v[10:13]
	v_mfma_f32_16x16x32_bf16 v[22:25], v[62:65], v[232:235], v[22:25]
	v_mfma_f32_16x16x32_bf16 v[6:9], v[78:81], v[232:235], v[6:9]
	v_mfma_f32_16x16x32_bf16 v[46:49], v[66:69], v[166:169], v[46:49]
	v_mfma_f32_16x16x32_bf16 v[38:41], v[82:85], v[166:169], v[38:41]
	v_mfma_f32_16x16x32_bf16 v[30:33], v[66:69], v[196:199], v[30:33]
	v_mfma_f32_16x16x32_bf16 v[14:17], v[82:85], v[196:199], v[14:17]
	v_mfma_f32_16x16x32_bf16 v[26:29], v[66:69], v[204:207], v[26:29]
	v_mfma_f32_16x16x32_bf16 v[10:13], v[82:85], v[204:207], v[10:13]
	v_mfma_f32_16x16x32_bf16 v[22:25], v[66:69], v[236:239], v[22:25]
	v_mfma_f32_16x16x32_bf16 v[6:9], v[82:85], v[236:239], v[6:9]
	s_setprio 0
	s_setprio 1
	v_mfma_f32_16x16x32_bf16 v[58:61], v[122:125], v[192:195], v[58:61]
	v_mfma_f32_16x16x32_bf16 v[50:53], v[154:157], v[192:195], v[50:53]
	v_mfma_f32_16x16x32_bf16 v[42:45], v[122:125], v[200:203], v[42:45]
	v_mfma_f32_16x16x32_bf16 v[34:37], v[154:157], v[200:203], v[34:37]
	v_mfma_f32_16x16x32_bf16 v[18:21], v[122:125], v[232:235], v[18:21]
	v_mfma_f32_16x16x32_bf16 v[2:5], v[154:157], v[232:235], v[2:5]
	v_mfma_f32_16x16x32_bf16 v[62:65], v[122:125], v[162:165], v[90:93]
	v_mfma_f32_16x16x32_bf16 v[66:69], v[154:157], v[162:165], v[74:77]
	v_mfma_f32_16x16x32_bf16 v[58:61], v[134:137], v[196:199], v[58:61]
	v_mfma_f32_16x16x32_bf16 v[50:53], v[158:161], v[196:199], v[50:53]
	v_mfma_f32_16x16x32_bf16 v[42:45], v[134:137], v[204:207], v[42:45]
	v_mfma_f32_16x16x32_bf16 v[34:37], v[158:161], v[204:207], v[34:37]
	v_mfma_f32_16x16x32_bf16 v[18:21], v[134:137], v[236:239], v[18:21]
	v_mfma_f32_16x16x32_bf16 v[2:5], v[158:161], v[236:239], v[2:5]
	v_mfma_f32_16x16x32_bf16 v[62:65], v[134:137], v[166:169], v[62:65]
	v_mfma_f32_16x16x32_bf16 v[66:69], v[158:161], v[166:169], v[66:69]
	s_setprio 0
	s_barrier
; #define PG8_STAGE(bufoff, gbase, voff) do { _Pragma("unroll") for (int _i = 0; _i < 2; ++_i) \
;         __builtin_amdgcn_global_load_lds((const unsigned*)((const char*)(gbase) + (voff)[_i]), (LAS unsigned*)(lds + (bufoff) + ldsw + _i * 8192), 16, 0, 0); } while (0)
; #define PG8_LDA(dst, b, h) do { _Pragma("unroll") for (int m = 0; m < 4; ++m) _Pragma("unroll") for (int k = 0; k < 2; ++k) dst[m][k] = *(const LAS bf16x8*)(lds + PG8_SA(b, h) + aoff + m * 2048 + k * 1024); } while (0)
; #define PG8_LDB(dst, b, h) do { _Pragma("unroll") for (int n = 0; n < 2; ++n) _Pragma("unroll") for (int k = 0; k < 2; ++k) dst[n][k] = *(const LAS bf16x8*)(lds + PG8_SB(b, h) + boff + n * 2048 + k * 1024); } while (0)
; #define PG8_MMA(ai, bj, At, Bt) do { __builtin_amdgcn_s_setprio(1); _Pragma("unroll") for (int m = 0; m < 4; ++m) _Pragma("unroll") for (int n = 0; n < 2; ++n) _Pragma("unroll") for (int k = 0; k < 2; ++k) \
;         acc[ai][bj][m][n] = __builtin_amdgcn_mfma_f32_16x16x32_bf16(Bt[n][k], At[m][k], acc[ai][bj][m][n], 0, 0, 0); __builtin_amdgcn_s_setprio(0); } while (0)
; #define PG8_WAIT_V(n) asm volatile("s_waitcnt vmcnt(" #n ")" ::: "memory")
; #define PG8_WAIT_L(n) asm volatile("s_waitcnt lgkmcnt(" #n ")" ::: "memory")
; #define PG8_BAR __builtin_amdgcn_s_barrier()
; #define PG8_SCHED __builtin_amdgcn_sched_barrier(0)
; template <bool ALIGN_EPI, class Epi, class Sched>
; DEV void gemm_phase(LAS unsigned char* lds, const Gemm g, const Sched& S, const Epi& E) {
;     ...
;             PG8_LDB(B0, 1, 0); PG8_LDB(B1, 1, 1); PG8_SCHED; PG8_LDA(At, 1, 0); PG8_STAGE(PG8_SA(0, 1), a2 + hstepA, voffA);
;             PG8_WAIT_V(8); PG8_WAIT_L(0); PG8_BAR; PG8_MMA(0, 0, At, B0); PG8_MMA(0, 1, At, B1); PG8_BAR; PG8_SCHED;
	s_add_i32 s24, 0, 0x18000
	s_add_i32 s25, 0, 0x1c000
	v_add_u32_e32 v90, s24, v171
	v_add_u32_e32 v158, s25, v171
	ds_read_b128 v[74:77], v90
	ds_read_b128 v[78:81], v90 offset:1024
	ds_read_b128 v[82:85], v90 offset:2048
	ds_read_b128 v[90:93], v90 offset:3072
	ds_read_b128 v[122:125], v158
	ds_read_b128 v[134:137], v158 offset:1024
	ds_read_b128 v[154:157], v158 offset:2048
	ds_read_b128 v[158:161], v158 offset:3072
	s_add_u32 s4, s92, 0x2000
	s_addc_u32 s5, s93, 0
	s_mov_b32 m0, s15
	v_lshl_add_u64 v[244:245], s[4:5], 0, v[184:185]
	ds_read_b128 v[162:165], v230 offset:32768
	ds_read_b128 v[166:169], v230 offset:33792
	ds_read_b128 v[192:195], v230 offset:34816
	ds_read_b128 v[196:199], v230 offset:35840
	ds_read_b128 v[200:203], v230 offset:36864
	ds_read_b128 v[204:207], v230 offset:37888
	ds_read_b128 v[232:235], v230 offset:38912
	ds_read_b128 v[236:239], v230 offset:39936
	global_load_lds_dwordx4 v[244:245], off
	v_lshl_add_u64 v[244:245], s[4:5], 0, v[182:183]
	s_mov_b32 m0, s17
	s_nop 0
	global_load_lds_dwordx4 v[244:245], off
	s_waitcnt vmcnt(8)
	s_waitcnt lgkmcnt(0)
	s_barrier
	s_setprio 1
	s_waitcnt lgkmcnt(0)
	v_mfma_f32_16x16x32_bf16 v[130:133], v[74:77], v[162:165], v[130:133]
	v_mfma_f32_16x16x32_bf16 v[118:121], v[82:85], v[162:165], v[118:121]
	v_mfma_f32_16x16x32_bf16 v[110:113], v[74:77], v[192:195], v[110:113]
	v_mfma_f32_16x16x32_bf16 v[102:105], v[82:85], v[192:195], v[102:105]
	v_mfma_f32_16x16x32_bf16 v[94:97], v[74:77], v[200:203], v[94:97]
	v_mfma_f32_16x16x32_bf16 v[86:89], v[82:85], v[200:203], v[86:89]
	v_mfma_f32_16x16x32_bf16 v[70:73], v[74:77], v[232:235], v[70:73]
	v_mfma_f32_16x16x32_bf16 v[54:57], v[82:85], v[232:235], v[54:57]
	v_mfma_f32_16x16x32_bf16 v[130:133], v[78:81], v[166:169], v[130:133]
	v_mfma_f32_16x16x32_bf16 v[118:121], v[90:93], v[166:169], v[118:121]
	v_mfma_f32_16x16x32_bf16 v[110:113], v[78:81], v[196:199], v[110:113]
	v_mfma_f32_16x16x32_bf16 v[102:105], v[90:93], v[196:199], v[102:105]
	v_mfma_f32_16x16x32_bf16 v[94:97], v[78:81], v[204:207], v[94:97]
	v_mfma_f32_16x16x32_bf16 v[86:89], v[90:93], v[204:207], v[86:89]
	v_mfma_f32_16x16x32_bf16 v[70:73], v[78:81], v[236:239], v[70:73]
	v_mfma_f32_16x16x32_bf16 v[54:57], v[90:93], v[236:239], v[54:57]
	s_setprio 0
	s_setprio 1
	v_mfma_f32_16x16x32_bf16 v[150:153], v[122:125], v[162:165], v[150:153]
	v_mfma_f32_16x16x32_bf16 v[146:149], v[154:157], v[162:165], v[146:149]
	v_mfma_f32_16x16x32_bf16 v[142:145], v[122:125], v[192:195], v[142:145]
	v_mfma_f32_16x16x32_bf16 v[138:141], v[154:157], v[192:195], v[138:141]
	v_mfma_f32_16x16x32_bf16 v[126:129], v[122:125], v[200:203], v[126:129]
	v_mfma_f32_16x16x32_bf16 v[114:117], v[154:157], v[200:203], v[114:117]
	v_mfma_f32_16x16x32_bf16 v[106:109], v[122:125], v[232:235], v[106:109]
	v_mfma_f32_16x16x32_bf16 v[98:101], v[154:157], v[232:235], v[98:101]
	v_mfma_f32_16x16x32_bf16 v[150:153], v[134:137], v[166:169], v[150:153]
	v_mfma_f32_16x16x32_bf16 v[146:149], v[158:161], v[166:169], v[146:149]
	v_mfma_f32_16x16x32_bf16 v[142:145], v[134:137], v[196:199], v[142:145]
	v_mfma_f32_16x16x32_bf16 v[138:141], v[158:161], v[196:199], v[138:141]
	v_mfma_f32_16x16x32_bf16 v[126:129], v[134:137], v[204:207], v[126:129]
	v_mfma_f32_16x16x32_bf16 v[114:117], v[158:161], v[204:207], v[114:117]
	v_mfma_f32_16x16x32_bf16 v[106:109], v[134:137], v[236:239], v[106:109]
	v_mfma_f32_16x16x32_bf16 v[98:101], v[158:161], v[236:239], v[98:101]
	s_setprio 0
	s_barrier
; #define PG8_STAGE(bufoff, gbase, voff) do { _Pragma("unroll") for (int _i = 0; _i < 2; ++_i) \
;         __builtin_amdgcn_global_load_lds((const unsigned*)((const char*)(gbase) + (voff)[_i]), (LAS unsigned*)(lds + (bufoff) + ldsw + _i * 8192), 16, 0, 0); } while (0)
; #define PG8_LDA(dst, b, h) do { _Pragma("unroll") for (int m = 0; m < 4; ++m) _Pragma("unroll") for (int k = 0; k < 2; ++k) dst[m][k] = *(const LAS bf16x8*)(lds + PG8_SA(b, h) + aoff + m * 2048 + k * 1024); } while (0)
; #define PG8_LDB(dst, b, h) do { _Pragma("unroll") for (int n = 0; n < 2; ++n) _Pragma("unroll") for (int k = 0; k < 2; ++k) dst[n][k] = *(const LAS bf16x8*)(lds + PG8_SB(b, h) + boff + n * 2048 + k * 1024); } while (0)
; #define PG8_WAIT_V(n) asm volatile("s_waitcnt vmcnt(" #n ")" ::: "memory")
; template <bool ALIGN_EPI, class Epi, class Sched>
; DEV void gemm_phase(LAS unsigned char* lds, const Gemm g, const Sched& S, const Epi& E) {
;     ...
;         for (int t = 0; t < nt; t += 2) {
;             const bool last = (t == nt - 2);
;             const char* a1 = cA + (size_t)(t + 1) * kstep;
;             const char* a2 = last ? nA : cA + (size_t)(t + 2) * kstep; const char* b2 = last ? nB : cB + (size_t)(t + 2) * kstep;
;             const char* a3 = a2 + kstep; const char* b3 = b2 + kstep;
;             PG8_LDB(B0, 0, 0); PG8_LDB(B1, 0, 1); PG8_SCHED; PG8_LDA(At, 0, 0); PG8_STAGE(PG8_SA(1, 1), a1 + hstepA, voffA);
;             PG8_WAIT_V(8); PG8_WAIT_L(0); PG8_BAR; PG8_MMA(0, 0, At, B0); PG8_MMA(0, 1, At, B1); PG8_BAR; PG8_SCHED;
;             PG8_LDA(At, 0, 1); PG8_STAGE(PG8_SB(0, 0), b2, voffB); PG8_STAGE(PG8_SB(0, 1), b2 + hstep, voffB); PG8_STAGE(PG8_SA(0, 0), a2, voffA);
;             PG8_WAIT_V(8); PG8_WAIT_L(0); PG8_BAR; PG8_MMA(1, 0, At, B0); PG8_MMA(1, 1, At, B1); PG8_BAR; PG8_SCHED;
;             PG8_LDB(B0, 1, 0); PG8_LDB(B1, 1, 1); PG8_SCHED; PG8_LDA(At, 1, 0); PG8_STAGE(PG8_SA(0, 1), a2 + hstepA, voffA);
;             PG8_WAIT_V(8); PG8_WAIT_L(0); PG8_BAR; PG8_MMA(0, 0, At, B0); PG8_MMA(0, 1, At, B1); PG8_BAR; PG8_SCHED;
;             PG8_LDA(At, 1, 1); PG8_STAGE(PG8_SB(1, 0), b3, voffB); PG8_STAGE(PG8_SB(1, 1), b3 + hstep, voffB); PG8_STAGE(PG8_SA(1, 0), a3, voffA);
;             PG8_WAIT_V(8); PG8_WAIT_L(0); PG8_BAR; PG8_MMA(1, 0, At, B0); PG8_MMA(1, 1, At, B1); PG8_BAR; PG8_SCHED;
;         }
;         if (ALIGN_EPI) { if (wr == 0) PG8_BAR; }
	s_add_i32 s4, s24, s8
	v_lshl_add_u64 v[208:209], v[208:209], 0, s[30:31]
	s_mov_b32 m0, s4
	ds_read_b128 v[162:165], v230 offset:49152
	ds_read_b128 v[166:169], v230 offset:50176
	ds_read_b128 v[192:195], v230 offset:51200
	ds_read_b128 v[196:199], v230 offset:52224
	ds_read_b128 v[200:203], v230 offset:53248
	ds_read_b128 v[204:207], v230 offset:54272
	ds_read_b128 v[232:235], v230 offset:55296
	ds_read_b128 v[236:239], v230 offset:56320
	global_load_lds_dwordx4 v[208:209], off
	s_add_i32 m0, s4, 0x2000
	s_add_u32 s4, s90, 0x40080
	v_lshl_add_u64 v[208:209], v[214:215], 0, s[30:31]
	s_addc_u32 s5, s91, 0
	s_add_i32 s24, s25, s8
	global_load_lds_dwordx4 v[208:209], off
	v_lshl_add_u64 v[208:209], s[4:5], 0, v[0:1]
	s_mov_b32 m0, s24
	s_nop 0
	global_load_lds_dwordx4 v[208:209], off
	v_lshl_add_u64 v[208:209], s[4:5], 0, v[180:181]
	s_add_i32 m0, s24, 0x2000
	s_nop 0
	global_load_lds_dwordx4 v[208:209], off
	v_lshl_add_u64 v[208:209], v[240:241], 0, s[30:31]
	s_mov_b32 m0, s94
	s_nop 0
	global_load_lds_dwordx4 v[208:209], off
	v_lshl_add_u64 v[208:209], v[242:243], 0, s[30:31]
	s_mov_b32 m0, s95
	s_nop 0
	global_load_lds_dwordx4 v[208:209], off
	s_waitcnt vmcnt(8)
	s_waitcnt lgkmcnt(0)
	s_barrier
	s_setprio 1
	s_waitcnt lgkmcnt(0)
	v_mfma_f32_16x16x32_bf16 v[46:49], v[74:77], v[162:165], v[46:49]
	v_mfma_f32_16x16x32_bf16 v[38:41], v[82:85], v[162:165], v[38:41]
	v_mfma_f32_16x16x32_bf16 v[30:33], v[74:77], v[192:195], v[30:33]
	v_mfma_f32_16x16x32_bf16 v[14:17], v[82:85], v[192:195], v[14:17]
	v_mfma_f32_16x16x32_bf16 v[26:29], v[74:77], v[200:203], v[26:29]
	v_mfma_f32_16x16x32_bf16 v[10:13], v[82:85], v[200:203], v[10:13]
	v_mfma_f32_16x16x32_bf16 v[22:25], v[74:77], v[232:235], v[22:25]
	v_mfma_f32_16x16x32_bf16 v[6:9], v[82:85], v[232:235], v[6:9]
	v_mfma_f32_16x16x32_bf16 v[46:49], v[78:81], v[166:169], v[46:49]
	v_mfma_f32_16x16x32_bf16 v[38:41], v[90:93], v[166:169], v[38:41]
	v_mfma_f32_16x16x32_bf16 v[30:33], v[78:81], v[196:199], v[30:33]
	v_mfma_f32_16x16x32_bf16 v[14:17], v[90:93], v[196:199], v[14:17]
	v_mfma_f32_16x16x32_bf16 v[26:29], v[78:81], v[204:207], v[26:29]
	v_mfma_f32_16x16x32_bf16 v[10:13], v[90:93], v[204:207], v[10:13]
	v_mfma_f32_16x16x32_bf16 v[22:25], v[78:81], v[236:239], v[22:25]
	v_mfma_f32_16x16x32_bf16 v[6:9], v[90:93], v[236:239], v[6:9]
	s_setprio 0
	s_setprio 1
	v_mfma_f32_16x16x32_bf16 v[62:65], v[122:125], v[162:165], v[62:65]
	v_mfma_f32_16x16x32_bf16 v[90:93], v[134:137], v[166:169], v[62:65]
	v_mfma_f32_16x16x32_bf16 v[62:65], v[154:157], v[162:165], v[66:69]
	v_mfma_f32_16x16x32_bf16 v[58:61], v[122:125], v[192:195], v[58:61]
	v_mfma_f32_16x16x32_bf16 v[50:53], v[154:157], v[192:195], v[50:53]
	v_mfma_f32_16x16x32_bf16 v[42:45], v[122:125], v[200:203], v[42:45]
	v_mfma_f32_16x16x32_bf16 v[34:37], v[154:157], v[200:203], v[34:37]
	v_mfma_f32_16x16x32_bf16 v[18:21], v[122:125], v[232:235], v[18:21]
	v_mfma_f32_16x16x32_bf16 v[2:5], v[154:157], v[232:235], v[2:5]
	v_mfma_f32_16x16x32_bf16 v[74:77], v[158:161], v[166:169], v[62:65]
	v_mfma_f32_16x16x32_bf16 v[58:61], v[134:137], v[196:199], v[58:61]
	v_mfma_f32_16x16x32_bf16 v[50:53], v[158:161], v[196:199], v[50:53]
	v_mfma_f32_16x16x32_bf16 v[42:45], v[134:137], v[204:207], v[42:45]
	v_mfma_f32_16x16x32_bf16 v[34:37], v[158:161], v[204:207], v[34:37]
	v_mfma_f32_16x16x32_bf16 v[18:21], v[134:137], v[236:239], v[18:21]
	v_mfma_f32_16x16x32_bf16 v[2:5], v[158:161], v[236:239], v[2:5]
	s_setprio 0
	s_add_i32 s49, s49, 2
	s_add_u32 s21, s21, 0x100
	s_addc_u32 s48, s48, 0
	s_cmp_gt_u32 s49, 13
	s_mov_b64 s[4:5], s[6:7]
	s_cbranch_scc1 .Lkx_28
	s_add_u32 s6, s4, 0x100
	s_addc_u32 s7, s5, 0
	s_add_i32 s24, 0, 0x10000
	s_cmp_eq_u32 s49, 12
	s_cselect_b32 s93, s85, s7
	s_cselect_b32 s92, vcc_lo, s6
	s_cselect_b32 s91, s83, s48
	s_cselect_b32 s90, vcc_hi, s21
	s_add_i32 s25, 0, 0x14000
	v_add_u32_e32 v82, s24, v171
	v_add_u32_e32 v158, s25, v171
	s_barrier
	s_branch .Lkr_28
.Lkx_28:
	s_barrier
	s_and_b64 vcc, exec, s[52:53]
	s_cbranch_vccz .LBB0_31
	s_barrier

; #define PG8_STAGE(bufoff, gbase, voff) do { _Pragma("unroll") for (int _i = 0; _i < 2; ++_i) \
;         __builtin_amdgcn_global_load_lds((const unsigned*)((const char*)(gbase) + (voff)[_i]), (LAS unsigned*)(lds + (bufoff) + ldsw + _i * 8192), 16, 0, 0); } while (0)
; #define PG8_LDA(dst, b, h) do { _Pragma("unroll") for (int m = 0; m < 4; ++m) _Pragma("unroll") for (int k = 0; k < 2; ++k) dst[m][k] = *(const LAS bf16x8*)(lds + PG8_SA(b, h) + aoff + m * 2048 + k * 1024); } while (0)
; #define PG8_LDB(dst, b, h) do { _Pragma("unroll") for (int n = 0; n < 2; ++n) _Pragma("unroll") for (int k = 0; k < 2; ++k) dst[n][k] = *(const LAS bf16x8*)(lds + PG8_SB(b, h) + boff + n * 2048 + k * 1024); } while (0)
; #define PG8_MMA(ai, bj, At, Bt) do { __builtin_amdgcn_s_setprio(1); _Pragma("unroll") for (int m = 0; m < 4; ++m) _Pragma("unroll") for (int n = 0; n < 2; ++n) _Pragma("unroll") for (int k = 0; k < 2; ++k) \
;         acc[ai][bj][m][n] = __builtin_amdgcn_mfma_f32_16x16x32_bf16(Bt[n][k], At[m][k], acc[ai][bj][m][n], 0, 0, 0); __builtin_amdgcn_s_setprio(0); } while (0)
; #define PG8_WAIT_V(n) asm volatile("s_waitcnt vmcnt(" #n ")" ::: "memory")
; #define PG8_WAIT_L(n) asm volatile("s_waitcnt lgkmcnt(" #n ")" ::: "memory")
; #define PG8_BAR __builtin_amdgcn_s_barrier()
; #define PG8_SCHED __builtin_amdgcn_sched_barrier(0)
; template <bool ALIGN_EPI, class Epi, class Sched>
; DEV void gemm_phase(LAS unsigned char* lds, const Gemm g, const Sched& S, const Epi& E) {
;     ...
;             PG8_LDB(B0, 0, 0); PG8_LDB(B1, 0, 1); PG8_SCHED; PG8_LDA(At, 0, 0); PG8_STAGE(PG8_SA(1, 1), a1 + hstepA, voffA);
;             PG8_WAIT_V(8); PG8_WAIT_L(0); PG8_BAR; PG8_MMA(0, 0, At, B0); PG8_MMA(0, 1, At, B1); PG8_BAR; PG8_SCHED;
;             PG8_LDA(At, 0, 1); PG8_STAGE(PG8_SB(0, 0), b2, voffB); PG8_STAGE(PG8_SB(0, 1), b2 + hstep, voffB); PG8_STAGE(PG8_SA(0, 0), a2, voffA);
;             PG8_WAIT_V(8); PG8_WAIT_L(0); PG8_BAR; PG8_MMA(1, 0, At, B0); PG8_MMA(1, 1, At, B1); PG8_BAR; PG8_SCHED;
.Lkr_69:
	ds_read_b128 v[130:133], v142
	ds_read_b128 v[134:137], v142 offset:1024
	ds_read_b128 v[138:141], v142 offset:2048
	ds_read_b128 v[142:145], v142 offset:3072
	ds_read_b128 v[146:149], v168
	ds_read_b128 v[150:153], v168 offset:1024
	ds_read_b128 v[164:167], v168 offset:2048
	ds_read_b128 v[180:183], v168 offset:3072
	v_lshl_add_u64 v[168:169], s[4:5], 0, v[160:161]
	s_add_i32 m0, s12, 0xc000
	ds_read_b128 v[190:193], v188
	ds_read_b128 v[194:197], v188 offset:1024
	ds_read_b128 v[198:201], v188 offset:2048
	ds_read_b128 v[202:205], v188 offset:3072
	ds_read_b128 v[206:209], v188 offset:4096
	ds_read_b128 v[230:233], v188 offset:5120
	ds_read_b128 v[234:237], v188 offset:6144
	ds_read_b128 v[238:241], v188 offset:7168
	global_load_lds_dwordx4 v[168:169], off
	v_lshl_add_u64 v[168:169], s[4:5], 0, v[162:163]
	s_add_i32 m0, s12, 0xe000
	s_nop 0
	global_load_lds_dwordx4 v[168:169], off
	s_waitcnt vmcnt(8)
	s_waitcnt lgkmcnt(0)
	s_barrier
	s_setprio 1
	s_waitcnt lgkmcnt(0)
	v_mfma_f32_16x16x32_bf16 v[126:129], v[130:133], v[190:193], v[126:129]
	v_mfma_f32_16x16x32_bf16 v[122:125], v[138:141], v[190:193], v[122:125]
	v_mfma_f32_16x16x32_bf16 v[110:113], v[130:133], v[198:201], v[110:113]
	v_mfma_f32_16x16x32_bf16 v[106:109], v[138:141], v[198:201], v[106:109]
	v_mfma_f32_16x16x32_bf16 v[98:101], v[130:133], v[206:209], v[98:101]
	v_mfma_f32_16x16x32_bf16 v[90:93], v[138:141], v[206:209], v[90:93]
	v_mfma_f32_16x16x32_bf16 v[82:85], v[130:133], v[234:237], v[82:85]
	v_mfma_f32_16x16x32_bf16 v[74:77], v[138:141], v[234:237], v[74:77]
	v_mfma_f32_16x16x32_bf16 v[126:129], v[134:137], v[194:197], v[126:129]
	v_mfma_f32_16x16x32_bf16 v[122:125], v[142:145], v[194:197], v[122:125]
	v_mfma_f32_16x16x32_bf16 v[110:113], v[134:137], v[202:205], v[110:113]
	v_mfma_f32_16x16x32_bf16 v[106:109], v[142:145], v[202:205], v[106:109]
	v_mfma_f32_16x16x32_bf16 v[98:101], v[134:137], v[230:233], v[98:101]
	v_mfma_f32_16x16x32_bf16 v[90:93], v[142:145], v[230:233], v[90:93]
	v_mfma_f32_16x16x32_bf16 v[82:85], v[134:137], v[238:241], v[82:85]
	v_mfma_f32_16x16x32_bf16 v[74:77], v[142:145], v[238:241], v[74:77]
	s_setprio 0
	s_setprio 1
	v_mfma_f32_16x16x32_bf16 v[118:121], v[146:149], v[190:193], v[118:121]
	v_mfma_f32_16x16x32_bf16 v[114:117], v[164:167], v[190:193], v[114:117]
	v_mfma_f32_16x16x32_bf16 v[102:105], v[146:149], v[198:201], v[102:105]
	v_mfma_f32_16x16x32_bf16 v[94:97], v[164:167], v[198:201], v[94:97]
	v_mfma_f32_16x16x32_bf16 v[86:89], v[146:149], v[206:209], v[86:89]
	v_mfma_f32_16x16x32_bf16 v[78:81], v[164:167], v[206:209], v[78:81]
	v_mfma_f32_16x16x32_bf16 v[70:73], v[146:149], v[234:237], v[70:73]
	v_mfma_f32_16x16x32_bf16 v[66:69], v[164:167], v[234:237], v[66:69]
	v_mfma_f32_16x16x32_bf16 v[118:121], v[150:153], v[194:197], v[118:121]
	v_mfma_f32_16x16x32_bf16 v[114:117], v[180:183], v[194:197], v[114:117]
	v_mfma_f32_16x16x32_bf16 v[102:105], v[150:153], v[202:205], v[102:105]
	v_mfma_f32_16x16x32_bf16 v[94:97], v[180:183], v[202:205], v[94:97]
	v_mfma_f32_16x16x32_bf16 v[86:89], v[150:153], v[230:233], v[86:89]
	v_mfma_f32_16x16x32_bf16 v[78:81], v[180:183], v[230:233], v[78:81]
	v_mfma_f32_16x16x32_bf16 v[70:73], v[150:153], v[238:241], v[70:73]
	v_mfma_f32_16x16x32_bf16 v[66:69], v[180:183], v[238:241], v[66:69]
	s_setprio 0
	s_barrier
	s_add_i32 s86, s86, s8
	v_lshl_add_u64 v[168:169], s[6:7], 0, v[0:1]
	s_mov_b32 m0, s86
	ds_read_b128 v[190:193], v188 offset:16384
	ds_read_b128 v[194:197], v188 offset:17408
	ds_read_b128 v[198:201], v188 offset:18432
	ds_read_b128 v[202:205], v188 offset:19456
	ds_read_b128 v[206:209], v188 offset:20480
	ds_read_b128 v[230:233], v188 offset:21504
	ds_read_b128 v[234:237], v188 offset:22528
	ds_read_b128 v[238:241], v188 offset:23552
	global_load_lds_dwordx4 v[168:169], off
	s_add_i32 m0, s86, 0x2000
	s_add_u32 s86, s6, 0x40000
	v_lshl_add_u64 v[184:185], s[6:7], 0, v[154:155]
	s_addc_u32 s87, s7, 0
	s_add_i32 s88, s88, s8
	global_load_lds_dwordx4 v[184:185], off
	v_lshl_add_u64 v[214:215], s[86:87], 0, v[0:1]
	s_mov_b32 m0, s88
	v_lshl_add_u64 v[228:229], s[78:79], 0, v[156:157]
	global_load_lds_dwordx4 v[214:215], off
	v_lshl_add_u64 v[214:215], s[86:87], 0, v[154:155]
	s_add_i32 m0, s88, 0x2000
	s_nop 0
	global_load_lds_dwordx4 v[214:215], off
	v_lshl_add_u64 v[214:215], s[78:79], 0, v[158:159]
	s_mov_b32 m0, s12
	s_nop 0
	global_load_lds_dwordx4 v[214:215], off
	s_mov_b32 m0, s13
	s_nop 0
	global_load_lds_dwordx4 v[228:229], off
	s_waitcnt vmcnt(8)
	s_waitcnt lgkmcnt(0)
	s_barrier
; #define PG8_STAGE(bufoff, gbase, voff) do { _Pragma("unroll") for (int _i = 0; _i < 2; ++_i) \
;         __builtin_amdgcn_global_load_lds((const unsigned*)((const char*)(gbase) + (voff)[_i]), (LAS unsigned*)(lds + (bufoff) + ldsw + _i * 8192), 16, 0, 0); } while (0)
; #define PG8_LDA(dst, b, h) do { _Pragma("unroll") for (int m = 0; m < 4; ++m) _Pragma("unroll") for (int k = 0; k < 2; ++k) dst[m][k] = *(const LAS bf16x8*)(lds + PG8_SA(b, h) + aoff + m * 2048 + k * 1024); } while (0)
; #define PG8_LDB(dst, b, h) do { _Pragma("unroll") for (int n = 0; n < 2; ++n) _Pragma("unroll") for (int k = 0; k < 2; ++k) dst[n][k] = *(const LAS bf16x8*)(lds + PG8_SB(b, h) + boff + n * 2048 + k * 1024); } while (0)
; #define PG8_MMA(ai, bj, At, Bt) do { __builtin_amdgcn_s_setprio(1); _Pragma("unroll") for (int m = 0; m < 4; ++m) _Pragma("unroll") for (int n = 0; n < 2; ++n) _Pragma("unroll") for (int k = 0; k < 2; ++k) \
;         acc[ai][bj][m][n] = __builtin_amdgcn_mfma_f32_16x16x32_bf16(Bt[n][k], At[m][k], acc[ai][bj][m][n], 0, 0, 0); __builtin_amdgcn_s_setprio(0); } while (0)
; #define PG8_WAIT_V(n) asm volatile("s_waitcnt vmcnt(" #n ")" ::: "memory")
; #define PG8_WAIT_L(n) asm volatile("s_waitcnt lgkmcnt(" #n ")" ::: "memory")
; #define PG8_BAR __builtin_amdgcn_s_barrier()
; #define PG8_SCHED __builtin_amdgcn_sched_barrier(0)
; template <bool ALIGN_EPI, class Epi, class Sched>
; DEV void gemm_phase(LAS unsigned char* lds, const Gemm g, const Sched& S, const Epi& E) {
;     ...
;             PG8_WAIT_V(8); PG8_WAIT_L(0); PG8_BAR; PG8_MMA(1, 0, At, B0); PG8_MMA(1, 1, At, B1); PG8_BAR; PG8_SCHED;
;             PG8_LDB(B0, 1, 0); PG8_LDB(B1, 1, 1); PG8_SCHED; PG8_LDA(At, 1, 0); PG8_STAGE(PG8_SA(0, 1), a2 + hstepA, voffA);
;             PG8_WAIT_V(8); PG8_WAIT_L(0); PG8_BAR; PG8_MMA(0, 0, At, B0); PG8_MMA(0, 1, At, B1); PG8_BAR; PG8_SCHED;
	s_setprio 1
	s_waitcnt lgkmcnt(0)
	v_mfma_f32_16x16x32_bf16 v[62:65], v[130:133], v[190:193], v[62:65]
	v_mfma_f32_16x16x32_bf16 v[58:61], v[138:141], v[190:193], v[58:61]
	v_mfma_f32_16x16x32_bf16 v[50:53], v[130:133], v[198:201], v[50:53]
	v_mfma_f32_16x16x32_bf16 v[42:45], v[138:141], v[198:201], v[42:45]
	v_mfma_f32_16x16x32_bf16 v[34:37], v[130:133], v[206:209], v[34:37]
	v_mfma_f32_16x16x32_bf16 v[26:29], v[138:141], v[206:209], v[26:29]
	v_mfma_f32_16x16x32_bf16 v[18:21], v[130:133], v[234:237], v[18:21]
	v_mfma_f32_16x16x32_bf16 v[10:13], v[138:141], v[234:237], v[10:13]
	v_mfma_f32_16x16x32_bf16 v[62:65], v[134:137], v[194:197], v[62:65]
	v_mfma_f32_16x16x32_bf16 v[58:61], v[142:145], v[194:197], v[58:61]
	v_mfma_f32_16x16x32_bf16 v[50:53], v[134:137], v[202:205], v[50:53]
	v_mfma_f32_16x16x32_bf16 v[42:45], v[142:145], v[202:205], v[42:45]
	v_mfma_f32_16x16x32_bf16 v[34:37], v[134:137], v[230:233], v[34:37]
	v_mfma_f32_16x16x32_bf16 v[26:29], v[142:145], v[230:233], v[26:29]
	v_mfma_f32_16x16x32_bf16 v[18:21], v[134:137], v[238:241], v[18:21]
	v_mfma_f32_16x16x32_bf16 v[10:13], v[142:145], v[238:241], v[10:13]
	s_setprio 0
	s_setprio 1
	v_mfma_f32_16x16x32_bf16 v[54:57], v[146:149], v[190:193], v[54:57]
	v_mfma_f32_16x16x32_bf16 v[46:49], v[164:167], v[190:193], v[46:49]
	v_mfma_f32_16x16x32_bf16 v[38:41], v[146:149], v[198:201], v[38:41]
	v_mfma_f32_16x16x32_bf16 v[30:33], v[164:167], v[198:201], v[30:33]
	v_mfma_f32_16x16x32_bf16 v[22:25], v[146:149], v[206:209], v[22:25]
	v_mfma_f32_16x16x32_bf16 v[14:17], v[164:167], v[206:209], v[14:17]
	v_mfma_f32_16x16x32_bf16 v[6:9], v[146:149], v[234:237], v[6:9]
	v_mfma_f32_16x16x32_bf16 v[2:5], v[164:167], v[234:237], v[2:5]
	v_mfma_f32_16x16x32_bf16 v[54:57], v[150:153], v[194:197], v[54:57]
	v_mfma_f32_16x16x32_bf16 v[46:49], v[180:183], v[194:197], v[46:49]
	v_mfma_f32_16x16x32_bf16 v[38:41], v[150:153], v[202:205], v[38:41]
	v_mfma_f32_16x16x32_bf16 v[30:33], v[180:183], v[202:205], v[30:33]
	v_mfma_f32_16x16x32_bf16 v[22:25], v[150:153], v[230:233], v[22:25]
	v_mfma_f32_16x16x32_bf16 v[14:17], v[180:183], v[230:233], v[14:17]
	v_mfma_f32_16x16x32_bf16 v[6:9], v[150:153], v[238:241], v[6:9]
	v_mfma_f32_16x16x32_bf16 v[2:5], v[180:183], v[238:241], v[2:5]
	s_setprio 0
	s_barrier
	s_add_i32 s86, 0, 0x18000
	s_add_i32 s87, 0, 0x1c000
	v_add_u32_e32 v142, s86, v186
	v_add_u32_e32 v180, s87, v186
	ds_read_b128 v[130:133], v142
	ds_read_b128 v[134:137], v142 offset:1024
	ds_read_b128 v[138:141], v142 offset:2048
	ds_read_b128 v[142:145], v142 offset:3072
	ds_read_b128 v[146:149], v180
	ds_read_b128 v[150:153], v180 offset:1024
	ds_read_b128 v[164:167], v180 offset:2048
	ds_read_b128 v[180:183], v180 offset:3072
	s_add_u32 s78, s78, 0x40000
	s_addc_u32 s79, s79, 0
	s_mov_b32 m0, s15
	v_lshl_add_u64 v[242:243], s[78:79], 0, v[158:159]
	ds_read_b128 v[190:193], v188 offset:32768
	ds_read_b128 v[194:197], v188 offset:33792
	ds_read_b128 v[198:201], v188 offset:34816
	ds_read_b128 v[202:205], v188 offset:35840
	ds_read_b128 v[206:209], v188 offset:36864
	ds_read_b128 v[230:233], v188 offset:37888
	ds_read_b128 v[234:237], v188 offset:38912
	ds_read_b128 v[238:241], v188 offset:39936
	global_load_lds_dwordx4 v[242:243], off
	v_lshl_add_u64 v[242:243], s[78:79], 0, v[156:157]
	s_mov_b32 m0, s17
	s_nop 0
	global_load_lds_dwordx4 v[242:243], off
	s_waitcnt vmcnt(8)
	s_waitcnt lgkmcnt(0)
	s_barrier
	s_setprio 1
	s_waitcnt lgkmcnt(0)
	v_mfma_f32_16x16x32_bf16 v[126:129], v[130:133], v[190:193], v[126:129]
	v_mfma_f32_16x16x32_bf16 v[122:125], v[138:141], v[190:193], v[122:125]
	v_mfma_f32_16x16x32_bf16 v[110:113], v[130:133], v[198:201], v[110:113]
	v_mfma_f32_16x16x32_bf16 v[106:109], v[138:141], v[198:201], v[106:109]
	v_mfma_f32_16x16x32_bf16 v[98:101], v[130:133], v[206:209], v[98:101]
	v_mfma_f32_16x16x32_bf16 v[90:93], v[138:141], v[206:209], v[90:93]
	v_mfma_f32_16x16x32_bf16 v[82:85], v[130:133], v[234:237], v[82:85]
	v_mfma_f32_16x16x32_bf16 v[74:77], v[138:141], v[234:237], v[74:77]
	v_mfma_f32_16x16x32_bf16 v[126:129], v[134:137], v[194:197], v[126:129]
	v_mfma_f32_16x16x32_bf16 v[122:125], v[142:145], v[194:197], v[122:125]
	v_mfma_f32_16x16x32_bf16 v[110:113], v[134:137], v[202:205], v[110:113]
	v_mfma_f32_16x16x32_bf16 v[106:109], v[142:145], v[202:205], v[106:109]
	v_mfma_f32_16x16x32_bf16 v[98:101], v[134:137], v[230:233], v[98:101]
	v_mfma_f32_16x16x32_bf16 v[90:93], v[142:145], v[230:233], v[90:93]
	v_mfma_f32_16x16x32_bf16 v[82:85], v[134:137], v[238:241], v[82:85]
	v_mfma_f32_16x16x32_bf16 v[74:77], v[142:145], v[238:241], v[74:77]
	s_setprio 0
	s_setprio 1
	v_mfma_f32_16x16x32_bf16 v[118:121], v[146:149], v[190:193], v[118:121]
	v_mfma_f32_16x16x32_bf16 v[114:117], v[164:167], v[190:193], v[114:117]
	v_mfma_f32_16x16x32_bf16 v[102:105], v[146:149], v[198:201], v[102:105]
	v_mfma_f32_16x16x32_bf16 v[94:97], v[164:167], v[198:201], v[94:97]
	v_mfma_f32_16x16x32_bf16 v[86:89], v[146:149], v[206:209], v[86:89]
	v_mfma_f32_16x16x32_bf16 v[78:81], v[164:167], v[206:209], v[78:81]
	v_mfma_f32_16x16x32_bf16 v[70:73], v[146:149], v[234:237], v[70:73]
	v_mfma_f32_16x16x32_bf16 v[66:69], v[164:167], v[234:237], v[66:69]
	v_mfma_f32_16x16x32_bf16 v[118:121], v[150:153], v[194:197], v[118:121]
	v_mfma_f32_16x16x32_bf16 v[114:117], v[180:183], v[194:197], v[114:117]
	v_mfma_f32_16x16x32_bf16 v[102:105], v[150:153], v[202:205], v[102:105]
	v_mfma_f32_16x16x32_bf16 v[94:97], v[180:183], v[202:205], v[94:97]
	v_mfma_f32_16x16x32_bf16 v[86:89], v[150:153], v[230:233], v[86:89]
	v_mfma_f32_16x16x32_bf16 v[78:81], v[180:183], v[230:233], v[78:81]
	v_mfma_f32_16x16x32_bf16 v[70:73], v[150:153], v[238:241], v[70:73]
	v_mfma_f32_16x16x32_bf16 v[66:69], v[180:183], v[238:241], v[66:69]
	s_setprio 0
	s_barrier
; #define PG8_STAGE(bufoff, gbase, voff) do { _Pragma("unroll") for (int _i = 0; _i < 2; ++_i) \
;         __builtin_amdgcn_global_load_lds((const unsigned*)((const char*)(gbase) + (voff)[_i]), (LAS unsigned*)(lds + (bufoff) + ldsw + _i * 8192), 16, 0, 0); } while (0)
; #define PG8_LDA(dst, b, h) do { _Pragma("unroll") for (int m = 0; m < 4; ++m) _Pragma("unroll") for (int k = 0; k < 2; ++k) dst[m][k] = *(const LAS bf16x8*)(lds + PG8_SA(b, h) + aoff + m * 2048 + k * 1024); } while (0)
; #define PG8_LDB(dst, b, h) do { _Pragma("unroll") for (int n = 0; n < 2; ++n) _Pragma("unroll") for (int k = 0; k < 2; ++k) dst[n][k] = *(const LAS bf16x8*)(lds + PG8_SB(b, h) + boff + n * 2048 + k * 1024); } while (0)
; #define PG8_WAIT_V(n) asm volatile("s_waitcnt vmcnt(" #n ")" ::: "memory")
; template <bool ALIGN_EPI, class Epi, class Sched>
; DEV void gemm_phase(LAS unsigned char* lds, const Gemm g, const Sched& S, const Epi& E) {
;     ...
;         for (int t = 0; t < nt; t += 2) {
;             const bool last = (t == nt - 2);
;             const char* a1 = cA + (size_t)(t + 1) * kstep;
;             const char* a2 = last ? nA : cA + (size_t)(t + 2) * kstep; const char* b2 = last ? nB : cB + (size_t)(t + 2) * kstep;
;             const char* a3 = a2 + kstep; const char* b3 = b2 + kstep;
;             PG8_LDB(B0, 0, 0); PG8_LDB(B1, 0, 1); PG8_SCHED; PG8_LDA(At, 0, 0); PG8_STAGE(PG8_SA(1, 1), a1 + hstepA, voffA);
;             PG8_WAIT_V(8); PG8_WAIT_L(0); PG8_BAR; PG8_MMA(0, 0, At, B0); PG8_MMA(0, 1, At, B1); PG8_BAR; PG8_SCHED;
;             PG8_LDA(At, 0, 1); PG8_STAGE(PG8_SB(0, 0), b2, voffB); PG8_STAGE(PG8_SB(0, 1), b2 + hstep, voffB); PG8_STAGE(PG8_SA(0, 0), a2, voffA);
;             PG8_WAIT_V(8); PG8_WAIT_L(0); PG8_BAR; PG8_MMA(1, 0, At, B0); PG8_MMA(1, 1, At, B1); PG8_BAR; PG8_SCHED;
;             PG8_LDB(B0, 1, 0); PG8_LDB(B1, 1, 1); PG8_SCHED; PG8_LDA(At, 1, 0); PG8_STAGE(PG8_SA(0, 1), a2 + hstepA, voffA);
;             PG8_WAIT_V(8); PG8_WAIT_L(0); PG8_BAR; PG8_MMA(0, 0, At, B0); PG8_MMA(0, 1, At, B1); PG8_BAR; PG8_SCHED;
;             PG8_LDA(At, 1, 1); PG8_STAGE(PG8_SB(1, 0), b3, voffB); PG8_STAGE(PG8_SB(1, 1), b3 + hstep, voffB); PG8_STAGE(PG8_SA(1, 0), a3, voffA);
;             PG8_WAIT_V(8); PG8_WAIT_L(0); PG8_BAR; PG8_MMA(1, 0, At, B0); PG8_MMA(1, 1, At, B1); PG8_BAR; PG8_SCHED;
;         }
;         if (ALIGN_EPI) { if (wr == 0) PG8_BAR; }
	s_add_i32 s78, s86, s8
	v_lshl_add_u64 v[168:169], v[168:169], 0, s[30:31]
	s_mov_b32 m0, s78
	ds_read_b128 v[190:193], v188 offset:49152
	ds_read_b128 v[194:197], v188 offset:50176
	ds_read_b128 v[198:201], v188 offset:51200
	ds_read_b128 v[202:205], v188 offset:52224
	ds_read_b128 v[206:209], v188 offset:53248
	ds_read_b128 v[230:233], v188 offset:54272
	ds_read_b128 v[234:237], v188 offset:55296
	ds_read_b128 v[238:241], v188 offset:56320
	global_load_lds_dwordx4 v[168:169], off
	s_add_i32 m0, s78, 0x2000
	s_add_u32 s6, s6, 0x40080
	v_lshl_add_u64 v[168:169], v[184:185], 0, s[30:31]
	s_addc_u32 s7, s7, 0
	s_add_i32 s78, s87, s8
	global_load_lds_dwordx4 v[168:169], off
	v_lshl_add_u64 v[168:169], s[6:7], 0, v[0:1]
	s_mov_b32 m0, s78
	s_nop 0
	global_load_lds_dwordx4 v[168:169], off
	v_lshl_add_u64 v[168:169], s[6:7], 0, v[154:155]
	s_add_i32 m0, s78, 0x2000
	s_nop 0
	global_load_lds_dwordx4 v[168:169], off
	v_lshl_add_u64 v[168:169], v[214:215], 0, s[30:31]
	s_mov_b32 m0, s20
	s_nop 0
	global_load_lds_dwordx4 v[168:169], off
	v_lshl_add_u64 v[168:169], v[228:229], 0, s[30:31]
	s_mov_b32 m0, s21
	s_nop 0
	global_load_lds_dwordx4 v[168:169], off
	s_waitcnt vmcnt(8)
	s_waitcnt lgkmcnt(0)
	s_barrier
	s_setprio 1
	s_waitcnt lgkmcnt(0)
	v_mfma_f32_16x16x32_bf16 v[62:65], v[130:133], v[190:193], v[62:65]
	v_mfma_f32_16x16x32_bf16 v[58:61], v[138:141], v[190:193], v[58:61]
	v_mfma_f32_16x16x32_bf16 v[50:53], v[130:133], v[198:201], v[50:53]
	v_mfma_f32_16x16x32_bf16 v[42:45], v[138:141], v[198:201], v[42:45]
	v_mfma_f32_16x16x32_bf16 v[34:37], v[130:133], v[206:209], v[34:37]
	v_mfma_f32_16x16x32_bf16 v[26:29], v[138:141], v[206:209], v[26:29]
	v_mfma_f32_16x16x32_bf16 v[18:21], v[130:133], v[234:237], v[18:21]
	v_mfma_f32_16x16x32_bf16 v[10:13], v[138:141], v[234:237], v[10:13]
	v_mfma_f32_16x16x32_bf16 v[62:65], v[134:137], v[194:197], v[62:65]
	v_mfma_f32_16x16x32_bf16 v[58:61], v[142:145], v[194:197], v[58:61]
	v_mfma_f32_16x16x32_bf16 v[50:53], v[134:137], v[202:205], v[50:53]
	v_mfma_f32_16x16x32_bf16 v[42:45], v[142:145], v[202:205], v[42:45]
	v_mfma_f32_16x16x32_bf16 v[34:37], v[134:137], v[230:233], v[34:37]
	v_mfma_f32_16x16x32_bf16 v[26:29], v[142:145], v[230:233], v[26:29]
	v_mfma_f32_16x16x32_bf16 v[18:21], v[134:137], v[238:241], v[18:21]
	v_mfma_f32_16x16x32_bf16 v[10:13], v[142:145], v[238:241], v[10:13]
	s_setprio 0
	s_setprio 1
	v_mfma_f32_16x16x32_bf16 v[54:57], v[146:149], v[190:193], v[54:57]
	v_mfma_f32_16x16x32_bf16 v[46:49], v[164:167], v[190:193], v[46:49]
	v_mfma_f32_16x16x32_bf16 v[38:41], v[146:149], v[198:201], v[38:41]
	v_mfma_f32_16x16x32_bf16 v[30:33], v[164:167], v[198:201], v[30:33]
	v_mfma_f32_16x16x32_bf16 v[22:25], v[146:149], v[206:209], v[22:25]
	v_mfma_f32_16x16x32_bf16 v[14:17], v[164:167], v[206:209], v[14:17]
	v_mfma_f32_16x16x32_bf16 v[6:9], v[146:149], v[234:237], v[6:9]
	v_mfma_f32_16x16x32_bf16 v[2:5], v[164:167], v[234:237], v[2:5]
	v_mfma_f32_16x16x32_bf16 v[54:57], v[150:153], v[194:197], v[54:57]
	v_mfma_f32_16x16x32_bf16 v[46:49], v[180:183], v[194:197], v[46:49]
	v_mfma_f32_16x16x32_bf16 v[38:41], v[150:153], v[202:205], v[38:41]
	v_mfma_f32_16x16x32_bf16 v[30:33], v[180:183], v[202:205], v[30:33]
	v_mfma_f32_16x16x32_bf16 v[22:25], v[150:153], v[230:233], v[22:25]
	v_mfma_f32_16x16x32_bf16 v[14:17], v[180:183], v[230:233], v[14:17]
	v_mfma_f32_16x16x32_bf16 v[6:9], v[150:153], v[238:241], v[6:9]
	v_mfma_f32_16x16x32_bf16 v[2:5], v[180:183], v[238:241], v[2:5]
	s_setprio 0
	s_add_i32 s85, s85, 2
	s_add_u32 s4, s4, 0x100
	s_addc_u32 s5, s5, 0
	s_add_u32 s83, s83, 0x100
	s_addc_u32 s84, s84, 0
	s_cmp_gt_u32 s85, 13
	s_cbranch_scc1 .Lkx_69
	s_add_u32 s6, s4, 0xfffc0080
	s_addc_u32 s7, s5, -1
	s_add_i32 s86, 0, 0x10000
	s_cmp_eq_u32 s85, 12
	s_cselect_b32 s79, s51, s7
	s_cselect_b32 s78, s81, s6
	s_cselect_b32 s7, s49, s84
	s_cselect_b32 s6, s82, s83
	s_add_i32 s88, 0, 0x14000
	v_add_u32_e32 v142, s86, v186
	v_add_u32_e32 v168, s88, v186
	s_barrier
	s_branch .Lkr_69
.Lkx_69:
	s_barrier
	s_and_b64 vcc, exec, s[44:45]
	s_cbranch_vccz .LBB0_72
	s_barrier

; #define PG8_STAGE(bufoff, gbase, voff) do { _Pragma("unroll") for (int _i = 0; _i < 2; ++_i) \
;         __builtin_amdgcn_global_load_lds((const unsigned*)((const char*)(gbase) + (voff)[_i]), (LAS unsigned*)(lds + (bufoff) + ldsw + _i * 8192), 16, 0, 0); } while (0)
; #define PG8_LDA(dst, b, h) do { _Pragma("unroll") for (int m = 0; m < 4; ++m) _Pragma("unroll") for (int k = 0; k < 2; ++k) dst[m][k] = *(const LAS bf16x8*)(lds + PG8_SA(b, h) + aoff + m * 2048 + k * 1024); } while (0)
; #define PG8_LDB(dst, b, h) do { _Pragma("unroll") for (int n = 0; n < 2; ++n) _Pragma("unroll") for (int k = 0; k < 2; ++k) dst[n][k] = *(const LAS bf16x8*)(lds + PG8_SB(b, h) + boff + n * 2048 + k * 1024); } while (0)
; #define PG8_MMA(ai, bj, At, Bt) do { __builtin_amdgcn_s_setprio(1); _Pragma("unroll") for (int m = 0; m < 4; ++m) _Pragma("unroll") for (int n = 0; n < 2; ++n) _Pragma("unroll") for (int k = 0; k < 2; ++k) \
;         acc[ai][bj][m][n] = __builtin_amdgcn_mfma_f32_16x16x32_bf16(Bt[n][k], At[m][k], acc[ai][bj][m][n], 0, 0, 0); __builtin_amdgcn_s_setprio(0); } while (0)
; #define PG8_WAIT_V(n) asm volatile("s_waitcnt vmcnt(" #n ")" ::: "memory")
; #define PG8_WAIT_L(n) asm volatile("s_waitcnt lgkmcnt(" #n ")" ::: "memory")
; #define PG8_BAR __builtin_amdgcn_s_barrier()
; #define PG8_SCHED __builtin_amdgcn_sched_barrier(0)
; template <bool ALIGN_EPI, class Epi, class Sched>
; DEV void gemm_phase(LAS unsigned char* lds, const Gemm g, const Sched& S, const Epi& E) {
;     ...
;             PG8_LDB(B0, 0, 0); PG8_LDB(B1, 0, 1); PG8_SCHED; PG8_LDA(At, 0, 0); PG8_STAGE(PG8_SA(1, 1), a1 + hstepA, voffA);
;             PG8_WAIT_V(8); PG8_WAIT_L(0); PG8_BAR; PG8_MMA(0, 0, At, B0); PG8_MMA(0, 1, At, B1); PG8_BAR; PG8_SCHED;
;             PG8_LDA(At, 0, 1); PG8_STAGE(PG8_SB(0, 0), b2, voffB); PG8_STAGE(PG8_SB(0, 1), b2 + hstep, voffB); PG8_STAGE(PG8_SA(0, 0), a2, voffA);
;             PG8_WAIT_V(8); PG8_WAIT_L(0); PG8_BAR; PG8_MMA(1, 0, At, B0); PG8_MMA(1, 1, At, B1); PG8_BAR; PG8_SCHED;
.Lkr_91:
	ds_read_b128 v[132:135], v0
	ds_read_b128 v[136:139], v0 offset:1024
	ds_read_b128 v[140:143], v0 offset:2048
	ds_read_b128 v[144:147], v0 offset:3072
	v_add_u32_e32 v0, s88, v198
	ds_read_b128 v[148:151], v0
	s_waitcnt lgkmcnt(0)
	ds_read_b128 v[152:155], v0 offset:1024
	ds_read_b128 v[156:159], v0 offset:2048
	ds_read_b128 v[160:163], v0 offset:3072
	v_lshl_add_u64 v[2:3], s[4:5], 0, v[186:187]
	s_add_i32 m0, s12, 0xc000
	ds_read_b128 v[164:167], v200
	ds_read_b128 v[190:193], v200 offset:1024
	ds_read_b128 v[194:197], v200 offset:2048
	ds_read_b128 v[202:205], v200 offset:3072
	ds_read_b128 v[206:209], v200 offset:4096
	ds_read_b128 v[230:233], v200 offset:5120
	ds_read_b128 v[234:237], v200 offset:6144
	ds_read_b128 v[238:241], v200 offset:7168
	global_load_lds_dwordx4 v[2:3], off
	v_lshl_add_u64 v[2:3], s[4:5], 0, v[188:189]
	s_add_i32 m0, s12, 0xe000
	s_nop 0
	global_load_lds_dwordx4 v[2:3], off
	s_waitcnt vmcnt(8)
	s_waitcnt lgkmcnt(0)
	s_barrier
	s_setprio 1
	s_waitcnt lgkmcnt(0)
	v_mfma_f32_16x16x32_bf16 v[128:131], v[132:135], v[164:167], v[128:131]
	v_mfma_f32_16x16x32_bf16 v[124:127], v[140:143], v[164:167], v[124:127]
	v_mfma_f32_16x16x32_bf16 v[120:123], v[132:135], v[194:197], v[120:123]
	v_mfma_f32_16x16x32_bf16 v[116:119], v[140:143], v[194:197], v[116:119]
	v_mfma_f32_16x16x32_bf16 v[112:115], v[132:135], v[206:209], v[112:115]
	v_mfma_f32_16x16x32_bf16 v[108:111], v[140:143], v[206:209], v[108:111]
	v_mfma_f32_16x16x32_bf16 v[104:107], v[132:135], v[234:237], v[104:107]
	v_mfma_f32_16x16x32_bf16 v[100:103], v[140:143], v[234:237], v[100:103]
	v_mfma_f32_16x16x32_bf16 v[128:131], v[136:139], v[190:193], v[128:131]
	v_mfma_f32_16x16x32_bf16 v[124:127], v[144:147], v[190:193], v[124:127]
	v_mfma_f32_16x16x32_bf16 v[120:123], v[136:139], v[202:205], v[120:123]
	v_mfma_f32_16x16x32_bf16 v[116:119], v[144:147], v[202:205], v[116:119]
	v_mfma_f32_16x16x32_bf16 v[112:115], v[136:139], v[230:233], v[112:115]
	v_mfma_f32_16x16x32_bf16 v[108:111], v[144:147], v[230:233], v[108:111]
	v_mfma_f32_16x16x32_bf16 v[104:107], v[136:139], v[238:241], v[104:107]
	v_mfma_f32_16x16x32_bf16 v[100:103], v[144:147], v[238:241], v[100:103]
	s_setprio 0
	s_setprio 1
	v_mfma_f32_16x16x32_bf16 v[96:99], v[148:151], v[164:167], v[96:99]
	v_mfma_f32_16x16x32_bf16 v[92:95], v[156:159], v[164:167], v[92:95]
	v_mfma_f32_16x16x32_bf16 v[88:91], v[148:151], v[194:197], v[88:91]
	v_mfma_f32_16x16x32_bf16 v[84:87], v[156:159], v[194:197], v[84:87]
	v_mfma_f32_16x16x32_bf16 v[80:83], v[148:151], v[206:209], v[80:83]
	v_mfma_f32_16x16x32_bf16 v[76:79], v[156:159], v[206:209], v[76:79]
	v_mfma_f32_16x16x32_bf16 v[72:75], v[148:151], v[234:237], v[72:75]
	v_mfma_f32_16x16x32_bf16 v[68:71], v[156:159], v[234:237], v[68:71]
	v_mfma_f32_16x16x32_bf16 v[96:99], v[152:155], v[190:193], v[96:99]
	v_mfma_f32_16x16x32_bf16 v[92:95], v[160:163], v[190:193], v[92:95]
	v_mfma_f32_16x16x32_bf16 v[88:91], v[152:155], v[202:205], v[88:91]
	v_mfma_f32_16x16x32_bf16 v[84:87], v[160:163], v[202:205], v[84:87]
	v_mfma_f32_16x16x32_bf16 v[80:83], v[152:155], v[230:233], v[80:83]
	v_mfma_f32_16x16x32_bf16 v[76:79], v[160:163], v[230:233], v[76:79]
	v_mfma_f32_16x16x32_bf16 v[72:75], v[152:155], v[238:241], v[72:75]
	v_mfma_f32_16x16x32_bf16 v[68:71], v[160:163], v[238:241], v[68:71]
	s_setprio 0
	s_barrier
	s_add_i32 s85, s85, s8
	v_lshl_add_u64 v[214:215], s[6:7], 0, v[182:183]
	s_mov_b32 m0, s85
	ds_read_b128 v[164:167], v200 offset:16384
	ds_read_b128 v[190:193], v200 offset:17408
	ds_read_b128 v[194:197], v200 offset:18432
	ds_read_b128 v[202:205], v200 offset:19456
	ds_read_b128 v[206:209], v200 offset:20480
	ds_read_b128 v[230:233], v200 offset:21504
	ds_read_b128 v[234:237], v200 offset:22528
	ds_read_b128 v[238:241], v200 offset:23552
	global_load_lds_dwordx4 v[214:215], off
	s_add_i32 m0, s85, 0x2000
	s_add_u32 s86, s6, 0x40000
	v_lshl_add_u64 v[228:229], s[6:7], 0, v[168:169]
	s_addc_u32 s87, s7, 0
	s_add_i32 s85, s88, s8
	global_load_lds_dwordx4 v[228:229], off
	v_lshl_add_u64 v[2:3], s[86:87], 0, v[182:183]
	s_mov_b32 m0, s85
	v_lshl_add_u64 v[242:243], s[42:43], 0, v[184:185]
	global_load_lds_dwordx4 v[2:3], off
	v_lshl_add_u64 v[2:3], s[86:87], 0, v[168:169]
	s_add_i32 m0, s85, 0x2000
	v_lshl_add_u64 v[244:245], s[42:43], 0, v[180:181]
	global_load_lds_dwordx4 v[2:3], off
	s_mov_b32 m0, s12
	s_nop 0
	global_load_lds_dwordx4 v[242:243], off
	s_mov_b32 m0, s13
	s_nop 0
	global_load_lds_dwordx4 v[244:245], off
	s_waitcnt vmcnt(8)
	s_waitcnt lgkmcnt(0)
	s_barrier
; #define PG8_STAGE(bufoff, gbase, voff) do { _Pragma("unroll") for (int _i = 0; _i < 2; ++_i) \
;         __builtin_amdgcn_global_load_lds((const unsigned*)((const char*)(gbase) + (voff)[_i]), (LAS unsigned*)(lds + (bufoff) + ldsw + _i * 8192), 16, 0, 0); } while (0)
; #define PG8_LDA(dst, b, h) do { _Pragma("unroll") for (int m = 0; m < 4; ++m) _Pragma("unroll") for (int k = 0; k < 2; ++k) dst[m][k] = *(const LAS bf16x8*)(lds + PG8_SA(b, h) + aoff + m * 2048 + k * 1024); } while (0)
; #define PG8_LDB(dst, b, h) do { _Pragma("unroll") for (int n = 0; n < 2; ++n) _Pragma("unroll") for (int k = 0; k < 2; ++k) dst[n][k] = *(const LAS bf16x8*)(lds + PG8_SB(b, h) + boff + n * 2048 + k * 1024); } while (0)
; #define PG8_MMA(ai, bj, At, Bt) do { __builtin_amdgcn_s_setprio(1); _Pragma("unroll") for (int m = 0; m < 4; ++m) _Pragma("unroll") for (int n = 0; n < 2; ++n) _Pragma("unroll") for (int k = 0; k < 2; ++k) \
;         acc[ai][bj][m][n] = __builtin_amdgcn_mfma_f32_16x16x32_bf16(Bt[n][k], At[m][k], acc[ai][bj][m][n], 0, 0, 0); __builtin_amdgcn_s_setprio(0); } while (0)
; #define PG8_WAIT_V(n) asm volatile("s_waitcnt vmcnt(" #n ")" ::: "memory")
; #define PG8_WAIT_L(n) asm volatile("s_waitcnt lgkmcnt(" #n ")" ::: "memory")
; #define PG8_BAR __builtin_amdgcn_s_barrier()
; #define PG8_SCHED __builtin_amdgcn_sched_barrier(0)
; template <bool ALIGN_EPI, class Epi, class Sched>
; DEV void gemm_phase(LAS unsigned char* lds, const Gemm g, const Sched& S, const Epi& E) {
;     ...
;             PG8_WAIT_V(8); PG8_WAIT_L(0); PG8_BAR; PG8_MMA(1, 0, At, B0); PG8_MMA(1, 1, At, B1); PG8_BAR; PG8_SCHED;
;             PG8_LDB(B0, 1, 0); PG8_LDB(B1, 1, 1); PG8_SCHED; PG8_LDA(At, 1, 0); PG8_STAGE(PG8_SA(0, 1), a2 + hstepA, voffA);
;             PG8_WAIT_V(8); PG8_WAIT_L(0); PG8_BAR; PG8_MMA(0, 0, At, B0); PG8_MMA(0, 1, At, B1); PG8_BAR; PG8_SCHED;
	s_setprio 1
	s_waitcnt lgkmcnt(0)
	v_mfma_f32_16x16x32_bf16 v[64:67], v[132:135], v[164:167], v[64:67]
	v_mfma_f32_16x16x32_bf16 v[60:63], v[140:143], v[164:167], v[60:63]
	v_mfma_f32_16x16x32_bf16 v[56:59], v[132:135], v[194:197], v[56:59]
	v_mfma_f32_16x16x32_bf16 v[52:55], v[140:143], v[194:197], v[52:55]
	v_mfma_f32_16x16x32_bf16 v[48:51], v[132:135], v[206:209], v[48:51]
	v_mfma_f32_16x16x32_bf16 v[44:47], v[140:143], v[206:209], v[44:47]
	v_mfma_f32_16x16x32_bf16 v[40:43], v[132:135], v[234:237], v[40:43]
	v_mfma_f32_16x16x32_bf16 v[36:39], v[140:143], v[234:237], v[36:39]
	v_mfma_f32_16x16x32_bf16 v[64:67], v[136:139], v[190:193], v[64:67]
	v_mfma_f32_16x16x32_bf16 v[60:63], v[144:147], v[190:193], v[60:63]
	v_mfma_f32_16x16x32_bf16 v[56:59], v[136:139], v[202:205], v[56:59]
	v_mfma_f32_16x16x32_bf16 v[52:55], v[144:147], v[202:205], v[52:55]
	v_mfma_f32_16x16x32_bf16 v[48:51], v[136:139], v[230:233], v[48:51]
	v_mfma_f32_16x16x32_bf16 v[44:47], v[144:147], v[230:233], v[44:47]
	v_mfma_f32_16x16x32_bf16 v[40:43], v[136:139], v[238:241], v[40:43]
	v_mfma_f32_16x16x32_bf16 v[36:39], v[144:147], v[238:241], v[36:39]
	s_setprio 0
	s_setprio 1
	v_mfma_f32_16x16x32_bf16 v[32:35], v[148:151], v[164:167], v[32:35]
	v_mfma_f32_16x16x32_bf16 v[28:31], v[156:159], v[164:167], v[28:31]
	v_mfma_f32_16x16x32_bf16 v[24:27], v[148:151], v[194:197], v[24:27]
	v_mfma_f32_16x16x32_bf16 v[20:23], v[156:159], v[194:197], v[20:23]
	v_mfma_f32_16x16x32_bf16 v[16:19], v[148:151], v[206:209], v[16:19]
	v_mfma_f32_16x16x32_bf16 v[12:15], v[156:159], v[206:209], v[12:15]
	v_mfma_f32_16x16x32_bf16 v[8:11], v[148:151], v[234:237], v[8:11]
	v_mfma_f32_16x16x32_bf16 v[2:5], v[156:159], v[234:237], v[4:7]
	v_mfma_f32_16x16x32_bf16 v[32:35], v[152:155], v[190:193], v[32:35]
	v_mfma_f32_16x16x32_bf16 v[28:31], v[160:163], v[190:193], v[28:31]
	v_mfma_f32_16x16x32_bf16 v[24:27], v[152:155], v[202:205], v[24:27]
	v_mfma_f32_16x16x32_bf16 v[20:23], v[160:163], v[202:205], v[20:23]
	v_mfma_f32_16x16x32_bf16 v[16:19], v[152:155], v[230:233], v[16:19]
	v_mfma_f32_16x16x32_bf16 v[12:15], v[160:163], v[230:233], v[12:15]
	v_mfma_f32_16x16x32_bf16 v[8:11], v[152:155], v[238:241], v[8:11]
	v_mfma_f32_16x16x32_bf16 v[2:5], v[160:163], v[238:241], v[2:5]
	s_setprio 0
	s_barrier
	s_add_i32 s85, 0, 0x18000
	v_add_u32_e32 v0, s85, v198
	s_add_i32 s86, 0, 0x1c000
	ds_read_b128 v[132:135], v0
	ds_read_b128 v[136:139], v0 offset:1024
	ds_read_b128 v[140:143], v0 offset:2048
	ds_read_b128 v[144:147], v0 offset:3072
	v_add_u32_e32 v0, s86, v198
	ds_read_b128 v[148:151], v0
	ds_read_b128 v[152:155], v0 offset:1024
	ds_read_b128 v[156:159], v0 offset:2048
	ds_read_b128 v[160:163], v0 offset:3072
	s_add_u32 s42, s42, 0x40000
	s_addc_u32 s43, s43, 0
	s_mov_b32 m0, s15
	v_lshl_add_u64 v[6:7], s[42:43], 0, v[184:185]
	ds_read_b128 v[164:167], v200 offset:32768
	ds_read_b128 v[190:193], v200 offset:33792
	ds_read_b128 v[194:197], v200 offset:34816
	ds_read_b128 v[202:205], v200 offset:35840
	ds_read_b128 v[206:209], v200 offset:36864
	ds_read_b128 v[230:233], v200 offset:37888
	ds_read_b128 v[234:237], v200 offset:38912
	ds_read_b128 v[238:241], v200 offset:39936
	global_load_lds_dwordx4 v[6:7], off
	v_lshl_add_u64 v[6:7], s[42:43], 0, v[180:181]
	s_mov_b32 m0, s17
	s_nop 0
	global_load_lds_dwordx4 v[6:7], off
	s_waitcnt vmcnt(8)
	s_waitcnt lgkmcnt(0)
	s_barrier
	s_setprio 1
	s_waitcnt lgkmcnt(0)
	v_mfma_f32_16x16x32_bf16 v[128:131], v[132:135], v[164:167], v[128:131]
	v_mfma_f32_16x16x32_bf16 v[124:127], v[140:143], v[164:167], v[124:127]
	v_mfma_f32_16x16x32_bf16 v[120:123], v[132:135], v[194:197], v[120:123]
	v_mfma_f32_16x16x32_bf16 v[116:119], v[140:143], v[194:197], v[116:119]
	v_mfma_f32_16x16x32_bf16 v[112:115], v[132:135], v[206:209], v[112:115]
	v_mfma_f32_16x16x32_bf16 v[108:111], v[140:143], v[206:209], v[108:111]
	v_mfma_f32_16x16x32_bf16 v[104:107], v[132:135], v[234:237], v[104:107]
	v_mfma_f32_16x16x32_bf16 v[100:103], v[140:143], v[234:237], v[100:103]
	v_mfma_f32_16x16x32_bf16 v[128:131], v[136:139], v[190:193], v[128:131]
	v_mfma_f32_16x16x32_bf16 v[124:127], v[144:147], v[190:193], v[124:127]
	v_mfma_f32_16x16x32_bf16 v[120:123], v[136:139], v[202:205], v[120:123]
	v_mfma_f32_16x16x32_bf16 v[116:119], v[144:147], v[202:205], v[116:119]
	v_mfma_f32_16x16x32_bf16 v[112:115], v[136:139], v[230:233], v[112:115]
	v_mfma_f32_16x16x32_bf16 v[108:111], v[144:147], v[230:233], v[108:111]
	v_mfma_f32_16x16x32_bf16 v[104:107], v[136:139], v[238:241], v[104:107]
	v_mfma_f32_16x16x32_bf16 v[100:103], v[144:147], v[238:241], v[100:103]
	s_setprio 0
	s_setprio 1
	v_mfma_f32_16x16x32_bf16 v[96:99], v[148:151], v[164:167], v[96:99]
	v_mfma_f32_16x16x32_bf16 v[92:95], v[156:159], v[164:167], v[92:95]
	v_mfma_f32_16x16x32_bf16 v[88:91], v[148:151], v[194:197], v[88:91]
	v_mfma_f32_16x16x32_bf16 v[84:87], v[156:159], v[194:197], v[84:87]
	v_mfma_f32_16x16x32_bf16 v[80:83], v[148:151], v[206:209], v[80:83]
	v_mfma_f32_16x16x32_bf16 v[76:79], v[156:159], v[206:209], v[76:79]
	v_mfma_f32_16x16x32_bf16 v[72:75], v[148:151], v[234:237], v[72:75]
	v_mfma_f32_16x16x32_bf16 v[68:71], v[156:159], v[234:237], v[68:71]
	v_mfma_f32_16x16x32_bf16 v[96:99], v[152:155], v[190:193], v[96:99]
	v_mfma_f32_16x16x32_bf16 v[92:95], v[160:163], v[190:193], v[92:95]
	v_mfma_f32_16x16x32_bf16 v[88:91], v[152:155], v[202:205], v[88:91]
	v_mfma_f32_16x16x32_bf16 v[84:87], v[160:163], v[202:205], v[84:87]
	v_mfma_f32_16x16x32_bf16 v[80:83], v[152:155], v[230:233], v[80:83]
	v_mfma_f32_16x16x32_bf16 v[76:79], v[160:163], v[230:233], v[76:79]
	v_mfma_f32_16x16x32_bf16 v[72:75], v[152:155], v[238:241], v[72:75]
	v_mfma_f32_16x16x32_bf16 v[68:71], v[160:163], v[238:241], v[68:71]
	s_setprio 0
	s_barrier
; #define PG8_STAGE(bufoff, gbase, voff) do { _Pragma("unroll") for (int _i = 0; _i < 2; ++_i) \
;         __builtin_amdgcn_global_load_lds((const unsigned*)((const char*)(gbase) + (voff)[_i]), (LAS unsigned*)(lds + (bufoff) + ldsw + _i * 8192), 16, 0, 0); } while (0)
; #define PG8_LDA(dst, b, h) do { _Pragma("unroll") for (int m = 0; m < 4; ++m) _Pragma("unroll") for (int k = 0; k < 2; ++k) dst[m][k] = *(const LAS bf16x8*)(lds + PG8_SA(b, h) + aoff + m * 2048 + k * 1024); } while (0)
; #define PG8_LDB(dst, b, h) do { _Pragma("unroll") for (int n = 0; n < 2; ++n) _Pragma("unroll") for (int k = 0; k < 2; ++k) dst[n][k] = *(const LAS bf16x8*)(lds + PG8_SB(b, h) + boff + n * 2048 + k * 1024); } while (0)
; #define PG8_WAIT_V(n) asm volatile("s_waitcnt vmcnt(" #n ")" ::: "memory")
; template <bool ALIGN_EPI, class Epi, class Sched>
; DEV void gemm_phase(LAS unsigned char* lds, const Gemm g, const Sched& S, const Epi& E) {
;     ...
;         for (int t = 0; t < nt; t += 2) {
;             const bool last = (t == nt - 2);
;             const char* a1 = cA + (size_t)(t + 1) * kstep;
;             const char* a2 = last ? nA : cA + (size_t)(t + 2) * kstep; const char* b2 = last ? nB : cB + (size_t)(t + 2) * kstep;
;             const char* a3 = a2 + kstep; const char* b3 = b2 + kstep;
;             PG8_LDB(B0, 0, 0); PG8_LDB(B1, 0, 1); PG8_SCHED; PG8_LDA(At, 0, 0); PG8_STAGE(PG8_SA(1, 1), a1 + hstepA, voffA);
;             PG8_WAIT_V(8); PG8_WAIT_L(0); PG8_BAR; PG8_MMA(0, 0, At, B0); PG8_MMA(0, 1, At, B1); PG8_BAR; PG8_SCHED;
;             PG8_LDA(At, 0, 1); PG8_STAGE(PG8_SB(0, 0), b2, voffB); PG8_STAGE(PG8_SB(0, 1), b2 + hstep, voffB); PG8_STAGE(PG8_SA(0, 0), a2, voffA);
;             PG8_WAIT_V(8); PG8_WAIT_L(0); PG8_BAR; PG8_MMA(1, 0, At, B0); PG8_MMA(1, 1, At, B1); PG8_BAR; PG8_SCHED;
;             PG8_LDB(B0, 1, 0); PG8_LDB(B1, 1, 1); PG8_SCHED; PG8_LDA(At, 1, 0); PG8_STAGE(PG8_SA(0, 1), a2 + hstepA, voffA);
;             PG8_WAIT_V(8); PG8_WAIT_L(0); PG8_BAR; PG8_MMA(0, 0, At, B0); PG8_MMA(0, 1, At, B1); PG8_BAR; PG8_SCHED;
;             PG8_LDA(At, 1, 1); PG8_STAGE(PG8_SB(1, 0), b3, voffB); PG8_STAGE(PG8_SB(1, 1), b3 + hstep, voffB); PG8_STAGE(PG8_SA(1, 0), a3, voffA);
;             PG8_WAIT_V(8); PG8_WAIT_L(0); PG8_BAR; PG8_MMA(1, 0, At, B0); PG8_MMA(1, 1, At, B1); PG8_BAR; PG8_SCHED;
;         }
;         if (ALIGN_EPI) { if (wr == 0) PG8_BAR; }
	s_add_i32 s42, s85, s8
	v_lshl_add_u64 v[6:7], v[214:215], 0, s[30:31]
	s_mov_b32 m0, s42
	ds_read_b128 v[164:167], v200 offset:49152
	ds_read_b128 v[190:193], v200 offset:50176
	ds_read_b128 v[194:197], v200 offset:51200
	ds_read_b128 v[202:205], v200 offset:52224
	ds_read_b128 v[206:209], v200 offset:53248
	ds_read_b128 v[230:233], v200 offset:54272
	ds_read_b128 v[234:237], v200 offset:55296
	ds_read_b128 v[238:241], v200 offset:56320
	global_load_lds_dwordx4 v[6:7], off
	s_add_i32 m0, s42, 0x2000
	s_add_u32 s6, s6, 0x40080
	v_lshl_add_u64 v[6:7], v[228:229], 0, s[30:31]
	s_addc_u32 s7, s7, 0
	s_add_i32 s42, s86, s8
	global_load_lds_dwordx4 v[6:7], off
	v_lshl_add_u64 v[6:7], s[6:7], 0, v[182:183]
	s_mov_b32 m0, s42
	s_nop 0
	global_load_lds_dwordx4 v[6:7], off
	v_lshl_add_u64 v[6:7], s[6:7], 0, v[168:169]
	s_add_i32 m0, s42, 0x2000
	s_nop 0
	global_load_lds_dwordx4 v[6:7], off
	v_lshl_add_u64 v[6:7], v[242:243], 0, s[30:31]
	s_mov_b32 m0, s20
	s_nop 0
	global_load_lds_dwordx4 v[6:7], off
	v_lshl_add_u64 v[6:7], v[244:245], 0, s[30:31]
	s_mov_b32 m0, s21
	s_nop 0
	global_load_lds_dwordx4 v[6:7], off
	s_waitcnt vmcnt(8)
	s_waitcnt lgkmcnt(0)
	s_barrier
	s_setprio 1
	s_waitcnt lgkmcnt(0)
	v_mfma_f32_16x16x32_bf16 v[64:67], v[132:135], v[164:167], v[64:67]
	v_mfma_f32_16x16x32_bf16 v[60:63], v[140:143], v[164:167], v[60:63]
	v_mfma_f32_16x16x32_bf16 v[56:59], v[132:135], v[194:197], v[56:59]
	v_mfma_f32_16x16x32_bf16 v[52:55], v[140:143], v[194:197], v[52:55]
	v_mfma_f32_16x16x32_bf16 v[48:51], v[132:135], v[206:209], v[48:51]
	v_mfma_f32_16x16x32_bf16 v[44:47], v[140:143], v[206:209], v[44:47]
	v_mfma_f32_16x16x32_bf16 v[40:43], v[132:135], v[234:237], v[40:43]
	v_mfma_f32_16x16x32_bf16 v[36:39], v[140:143], v[234:237], v[36:39]
	v_mfma_f32_16x16x32_bf16 v[64:67], v[136:139], v[190:193], v[64:67]
	v_mfma_f32_16x16x32_bf16 v[60:63], v[144:147], v[190:193], v[60:63]
	v_mfma_f32_16x16x32_bf16 v[56:59], v[136:139], v[202:205], v[56:59]
	v_mfma_f32_16x16x32_bf16 v[52:55], v[144:147], v[202:205], v[52:55]
	v_mfma_f32_16x16x32_bf16 v[48:51], v[136:139], v[230:233], v[48:51]
	v_mfma_f32_16x16x32_bf16 v[44:47], v[144:147], v[230:233], v[44:47]
	v_mfma_f32_16x16x32_bf16 v[40:43], v[136:139], v[238:241], v[40:43]
	v_mfma_f32_16x16x32_bf16 v[36:39], v[144:147], v[238:241], v[36:39]
	s_setprio 0
	s_setprio 1
	v_mfma_f32_16x16x32_bf16 v[32:35], v[148:151], v[164:167], v[32:35]
	v_mfma_f32_16x16x32_bf16 v[28:31], v[156:159], v[164:167], v[28:31]
	v_mfma_f32_16x16x32_bf16 v[24:27], v[148:151], v[194:197], v[24:27]
	v_mfma_f32_16x16x32_bf16 v[20:23], v[156:159], v[194:197], v[20:23]
	v_mfma_f32_16x16x32_bf16 v[16:19], v[148:151], v[206:209], v[16:19]
	v_mfma_f32_16x16x32_bf16 v[12:15], v[156:159], v[206:209], v[12:15]
	v_mfma_f32_16x16x32_bf16 v[6:9], v[148:151], v[234:237], v[8:11]
	v_mfma_f32_16x16x32_bf16 v[2:5], v[156:159], v[234:237], v[2:5]
	v_mfma_f32_16x16x32_bf16 v[32:35], v[152:155], v[190:193], v[32:35]
	v_mfma_f32_16x16x32_bf16 v[28:31], v[160:163], v[190:193], v[28:31]
	v_mfma_f32_16x16x32_bf16 v[24:27], v[152:155], v[202:205], v[24:27]
	v_mfma_f32_16x16x32_bf16 v[20:23], v[160:163], v[202:205], v[20:23]
	v_mfma_f32_16x16x32_bf16 v[16:19], v[152:155], v[230:233], v[16:19]
	v_mfma_f32_16x16x32_bf16 v[12:15], v[160:163], v[230:233], v[12:15]
	v_mfma_f32_16x16x32_bf16 v[8:11], v[152:155], v[238:241], v[6:9]
	v_mfma_f32_16x16x32_bf16 v[4:7], v[160:163], v[238:241], v[2:5]
	s_setprio 0
	s_add_i32 s84, s84, 2
	s_add_u32 s4, s4, 0x100
	s_addc_u32 s5, s5, 0
	s_add_u32 s82, s82, 0x100
	s_addc_u32 s83, s83, 0
	s_cmp_gt_u32 s84, 13
	s_cbranch_scc1 .Lkx_91
	s_add_u32 s6, s4, 0xfffc0080
	s_addc_u32 s7, s5, -1
	s_add_i32 s85, 0, 0x10000
	s_cmp_eq_u32 s84, 12
	s_cselect_b32 s43, s51, s7
	s_cselect_b32 s42, s80, s6
	v_add_u32_e32 v0, s85, v198
	s_cselect_b32 s7, s53, s83
	s_cselect_b32 s6, s81, s82
	s_add_i32 s88, 0, 0x14000
	s_barrier
	s_branch .Lkr_91
.Lkx_91:
	s_barrier
	s_and_b64 vcc, exec, s[48:49]
	s_cbranch_vccz .LBB0_94
	s_barrier

; #define PG8_STAGE(bufoff, gbase, voff) do { _Pragma("unroll") for (int _i = 0; _i < 2; ++_i) \
;         __builtin_amdgcn_global_load_lds((const unsigned*)((const char*)(gbase) + (voff)[_i]), (LAS unsigned*)(lds + (bufoff) + ldsw + _i * 8192), 16, 0, 0); } while (0)
; #define PG8_LDA(dst, b, h) do { _Pragma("unroll") for (int m = 0; m < 4; ++m) _Pragma("unroll") for (int k = 0; k < 2; ++k) dst[m][k] = *(const LAS bf16x8*)(lds + PG8_SA(b, h) + aoff + m * 2048 + k * 1024); } while (0)
; #define PG8_LDB(dst, b, h) do { _Pragma("unroll") for (int n = 0; n < 2; ++n) _Pragma("unroll") for (int k = 0; k < 2; ++k) dst[n][k] = *(const LAS bf16x8*)(lds + PG8_SB(b, h) + boff + n * 2048 + k * 1024); } while (0)
; #define PG8_MMA(ai, bj, At, Bt) do { __builtin_amdgcn_s_setprio(1); _Pragma("unroll") for (int m = 0; m < 4; ++m) _Pragma("unroll") for (int n = 0; n < 2; ++n) _Pragma("unroll") for (int k = 0; k < 2; ++k) \
;         acc[ai][bj][m][n] = __builtin_amdgcn_mfma_f32_16x16x32_bf16(Bt[n][k], At[m][k], acc[ai][bj][m][n], 0, 0, 0); __builtin_amdgcn_s_setprio(0); } while (0)
; #define PG8_WAIT_V(n) asm volatile("s_waitcnt vmcnt(" #n ")" ::: "memory")
; #define PG8_WAIT_L(n) asm volatile("s_waitcnt lgkmcnt(" #n ")" ::: "memory")
; #define PG8_BAR __builtin_amdgcn_s_barrier()
; #define PG8_SCHED __builtin_amdgcn_sched_barrier(0)
; template <bool ALIGN_EPI, class Epi, class Sched>
; DEV void gemm_phase(LAS unsigned char* lds, const Gemm g, const Sched& S, const Epi& E) {
;     ...
;             PG8_LDB(B0, 0, 0); PG8_LDB(B1, 0, 1); PG8_SCHED; PG8_LDA(At, 0, 0); PG8_STAGE(PG8_SA(1, 1), a1 + hstepA, voffA);
;             PG8_WAIT_V(8); PG8_WAIT_L(0); PG8_BAR; PG8_MMA(0, 0, At, B0); PG8_MMA(0, 1, At, B1); PG8_BAR; PG8_SCHED;
;             PG8_LDA(At, 0, 1); PG8_STAGE(PG8_SB(0, 0), b2, voffB); PG8_STAGE(PG8_SB(0, 1), b2 + hstep, voffB); PG8_STAGE(PG8_SA(0, 0), a2, voffA);
;             PG8_WAIT_V(8); PG8_WAIT_L(0); PG8_BAR; PG8_MMA(1, 0, At, B0); PG8_MMA(1, 1, At, B1); PG8_BAR; PG8_SCHED;
.Lkr_315:
	ds_read_b128 v[130:133], v0
	ds_read_b128 v[134:137], v0 offset:1024
	ds_read_b128 v[138:141], v0 offset:2048
	ds_read_b128 v[142:145], v0 offset:3072
	v_add_u32_e32 v0, vcc_lo, v171
	ds_read_b128 v[146:149], v0
	ds_read_b128 v[150:153], v0 offset:1024
	ds_read_b128 v[154:157], v0 offset:2048
	ds_read_b128 v[158:161], v0 offset:3072
	v_lshl_add_u64 v[246:247], s[4:5], 0, v[190:191]
	s_add_i32 m0, s13, 0xc000
	ds_read_b128 v[162:165], v203
	ds_read_b128 v[166:169], v203 offset:1024
	ds_read_b128 v[194:197], v203 offset:2048
	ds_read_b128 v[206:209], v203 offset:3072
	ds_read_b128 v[230:233], v203 offset:4096
	ds_read_b128 v[234:237], v203 offset:5120
	ds_read_b128 v[238:241], v203 offset:6144
	ds_read_b128 v[242:245], v203 offset:7168
	global_load_lds_dwordx4 v[246:247], off
	v_lshl_add_u64 v[246:247], s[4:5], 0, v[192:193]
	s_add_i32 m0, s13, 0xe000
	s_nop 0
	global_load_lds_dwordx4 v[246:247], off
	s_waitcnt vmcnt(8)
	s_waitcnt lgkmcnt(0)
	s_barrier
	s_setprio 1
	s_waitcnt lgkmcnt(0)
	v_mfma_f32_16x16x32_bf16 v[126:129], v[130:133], v[162:165], v[126:129]
	v_mfma_f32_16x16x32_bf16 v[122:125], v[138:141], v[162:165], v[122:125]
	v_mfma_f32_16x16x32_bf16 v[110:113], v[130:133], v[194:197], v[110:113]
	v_mfma_f32_16x16x32_bf16 v[106:109], v[138:141], v[194:197], v[106:109]
	v_mfma_f32_16x16x32_bf16 v[94:97], v[130:133], v[230:233], v[94:97]
	v_mfma_f32_16x16x32_bf16 v[90:93], v[138:141], v[230:233], v[90:93]
	v_mfma_f32_16x16x32_bf16 v[78:81], v[130:133], v[238:241], v[78:81]
	v_mfma_f32_16x16x32_bf16 v[74:77], v[138:141], v[238:241], v[74:77]
	v_mfma_f32_16x16x32_bf16 v[126:129], v[134:137], v[166:169], v[126:129]
	v_mfma_f32_16x16x32_bf16 v[122:125], v[142:145], v[166:169], v[122:125]
	v_mfma_f32_16x16x32_bf16 v[110:113], v[134:137], v[206:209], v[110:113]
	v_mfma_f32_16x16x32_bf16 v[106:109], v[142:145], v[206:209], v[106:109]
	v_mfma_f32_16x16x32_bf16 v[94:97], v[134:137], v[234:237], v[94:97]
	v_mfma_f32_16x16x32_bf16 v[90:93], v[142:145], v[234:237], v[90:93]
	v_mfma_f32_16x16x32_bf16 v[78:81], v[134:137], v[242:245], v[78:81]
	v_mfma_f32_16x16x32_bf16 v[74:77], v[142:145], v[242:245], v[74:77]
	s_setprio 0
	s_setprio 1
	v_mfma_f32_16x16x32_bf16 v[118:121], v[146:149], v[162:165], v[118:121]
	v_mfma_f32_16x16x32_bf16 v[114:117], v[154:157], v[162:165], v[114:117]
	v_mfma_f32_16x16x32_bf16 v[102:105], v[146:149], v[194:197], v[102:105]
	v_mfma_f32_16x16x32_bf16 v[98:101], v[154:157], v[194:197], v[98:101]
	v_mfma_f32_16x16x32_bf16 v[86:89], v[146:149], v[230:233], v[86:89]
	v_mfma_f32_16x16x32_bf16 v[82:85], v[154:157], v[230:233], v[82:85]
	v_mfma_f32_16x16x32_bf16 v[70:73], v[146:149], v[238:241], v[70:73]
	v_mfma_f32_16x16x32_bf16 v[66:69], v[154:157], v[238:241], v[66:69]
	v_mfma_f32_16x16x32_bf16 v[118:121], v[150:153], v[166:169], v[118:121]
	v_mfma_f32_16x16x32_bf16 v[114:117], v[158:161], v[166:169], v[114:117]
	v_mfma_f32_16x16x32_bf16 v[102:105], v[150:153], v[206:209], v[102:105]
	v_mfma_f32_16x16x32_bf16 v[98:101], v[158:161], v[206:209], v[98:101]
	v_mfma_f32_16x16x32_bf16 v[86:89], v[150:153], v[234:237], v[86:89]
	v_mfma_f32_16x16x32_bf16 v[82:85], v[158:161], v[234:237], v[82:85]
	v_mfma_f32_16x16x32_bf16 v[70:73], v[150:153], v[242:245], v[70:73]
	v_mfma_f32_16x16x32_bf16 v[66:69], v[158:161], v[242:245], v[66:69]
	s_setprio 0
	s_barrier
	s_add_i32 s4, s93, s12
	v_lshl_add_u64 v[246:247], s[46:47], 0, v[184:185]
	s_mov_b32 m0, s4
	ds_read_b128 v[162:165], v203 offset:16384
	ds_read_b128 v[166:169], v203 offset:17408
	ds_read_b128 v[194:197], v203 offset:18432
	ds_read_b128 v[206:209], v203 offset:19456
	ds_read_b128 v[230:233], v203 offset:20480
	ds_read_b128 v[234:237], v203 offset:21504
	ds_read_b128 v[238:241], v203 offset:22528
	ds_read_b128 v[242:245], v203 offset:23552
	global_load_lds_dwordx4 v[246:247], off
	s_add_i32 m0, s4, 0x2000
	s_add_u32 s4, s46, 0x40000
	v_lshl_add_u64 v[248:249], s[46:47], 0, v[180:181]
	s_addc_u32 s5, s47, 0
	s_add_i32 s93, vcc_lo, s12
	global_load_lds_dwordx4 v[248:249], off
	v_lshl_add_u64 v[250:251], s[4:5], 0, v[184:185]
	s_mov_b32 m0, s93
	v_lshl_add_u64 v[228:229], s[94:95], 0, v[182:183]
	global_load_lds_dwordx4 v[250:251], off
	v_lshl_add_u64 v[250:251], s[4:5], 0, v[180:181]
	s_add_i32 m0, s93, 0x2000
	s_nop 0
	global_load_lds_dwordx4 v[250:251], off
	v_lshl_add_u64 v[250:251], s[94:95], 0, v[186:187]
	s_mov_b32 m0, s13
	s_nop 0
	global_load_lds_dwordx4 v[250:251], off
	s_mov_b32 m0, s15
	s_nop 0
	global_load_lds_dwordx4 v[228:229], off
	s_waitcnt vmcnt(8)
	s_waitcnt lgkmcnt(0)
	s_barrier
; #define PG8_STAGE(bufoff, gbase, voff) do { _Pragma("unroll") for (int _i = 0; _i < 2; ++_i) \
;         __builtin_amdgcn_global_load_lds((const unsigned*)((const char*)(gbase) + (voff)[_i]), (LAS unsigned*)(lds + (bufoff) + ldsw + _i * 8192), 16, 0, 0); } while (0)
; #define PG8_LDA(dst, b, h) do { _Pragma("unroll") for (int m = 0; m < 4; ++m) _Pragma("unroll") for (int k = 0; k < 2; ++k) dst[m][k] = *(const LAS bf16x8*)(lds + PG8_SA(b, h) + aoff + m * 2048 + k * 1024); } while (0)
; #define PG8_LDB(dst, b, h) do { _Pragma("unroll") for (int n = 0; n < 2; ++n) _Pragma("unroll") for (int k = 0; k < 2; ++k) dst[n][k] = *(const LAS bf16x8*)(lds + PG8_SB(b, h) + boff + n * 2048 + k * 1024); } while (0)
; #define PG8_MMA(ai, bj, At, Bt) do { __builtin_amdgcn_s_setprio(1); _Pragma("unroll") for (int m = 0; m < 4; ++m) _Pragma("unroll") for (int n = 0; n < 2; ++n) _Pragma("unroll") for (int k = 0; k < 2; ++k) \
;         acc[ai][bj][m][n] = __builtin_amdgcn_mfma_f32_16x16x32_bf16(Bt[n][k], At[m][k], acc[ai][bj][m][n], 0, 0, 0); __builtin_amdgcn_s_setprio(0); } while (0)
; #define PG8_WAIT_V(n) asm volatile("s_waitcnt vmcnt(" #n ")" ::: "memory")
; #define PG8_WAIT_L(n) asm volatile("s_waitcnt lgkmcnt(" #n ")" ::: "memory")
; #define PG8_BAR __builtin_amdgcn_s_barrier()
; #define PG8_SCHED __builtin_amdgcn_sched_barrier(0)
; template <bool ALIGN_EPI, class Epi, class Sched>
; DEV void gemm_phase(LAS unsigned char* lds, const Gemm g, const Sched& S, const Epi& E) {
;     ...
;             PG8_WAIT_V(8); PG8_WAIT_L(0); PG8_BAR; PG8_MMA(1, 0, At, B0); PG8_MMA(1, 1, At, B1); PG8_BAR; PG8_SCHED;
;             PG8_LDB(B0, 1, 0); PG8_LDB(B1, 1, 1); PG8_SCHED; PG8_LDA(At, 1, 0); PG8_STAGE(PG8_SA(0, 1), a2 + hstepA, voffA);
;             PG8_WAIT_V(8); PG8_WAIT_L(0); PG8_BAR; PG8_MMA(0, 0, At, B0); PG8_MMA(0, 1, At, B1); PG8_BAR; PG8_SCHED;
	s_setprio 1
	s_waitcnt lgkmcnt(0)
	v_mfma_f32_16x16x32_bf16 v[62:65], v[130:133], v[162:165], v[62:65]
	v_mfma_f32_16x16x32_bf16 v[58:61], v[138:141], v[162:165], v[58:61]
	v_mfma_f32_16x16x32_bf16 v[46:49], v[130:133], v[194:197], v[46:49]
	v_mfma_f32_16x16x32_bf16 v[42:45], v[138:141], v[194:197], v[42:45]
	v_mfma_f32_16x16x32_bf16 v[30:33], v[130:133], v[230:233], v[30:33]
	v_mfma_f32_16x16x32_bf16 v[26:29], v[138:141], v[230:233], v[26:29]
	v_mfma_f32_16x16x32_bf16 v[14:17], v[130:133], v[238:241], v[14:17]
	v_mfma_f32_16x16x32_bf16 v[10:13], v[138:141], v[238:241], v[10:13]
	v_mfma_f32_16x16x32_bf16 v[62:65], v[134:137], v[166:169], v[62:65]
	v_mfma_f32_16x16x32_bf16 v[58:61], v[142:145], v[166:169], v[58:61]
	v_mfma_f32_16x16x32_bf16 v[46:49], v[134:137], v[206:209], v[46:49]
	v_mfma_f32_16x16x32_bf16 v[42:45], v[142:145], v[206:209], v[42:45]
	v_mfma_f32_16x16x32_bf16 v[30:33], v[134:137], v[234:237], v[30:33]
	v_mfma_f32_16x16x32_bf16 v[26:29], v[142:145], v[234:237], v[26:29]
	v_mfma_f32_16x16x32_bf16 v[14:17], v[134:137], v[242:245], v[14:17]
	v_mfma_f32_16x16x32_bf16 v[10:13], v[142:145], v[242:245], v[10:13]
	s_setprio 0
	s_setprio 1
	v_mfma_f32_16x16x32_bf16 v[54:57], v[146:149], v[162:165], v[54:57]
	v_mfma_f32_16x16x32_bf16 v[50:53], v[154:157], v[162:165], v[50:53]
	v_mfma_f32_16x16x32_bf16 v[38:41], v[146:149], v[194:197], v[38:41]
	v_mfma_f32_16x16x32_bf16 v[34:37], v[154:157], v[194:197], v[34:37]
	v_mfma_f32_16x16x32_bf16 v[22:25], v[146:149], v[230:233], v[22:25]
	v_mfma_f32_16x16x32_bf16 v[18:21], v[154:157], v[230:233], v[18:21]
	v_mfma_f32_16x16x32_bf16 v[6:9], v[146:149], v[238:241], v[6:9]
	v_mfma_f32_16x16x32_bf16 v[2:5], v[154:157], v[238:241], v[2:5]
	v_mfma_f32_16x16x32_bf16 v[54:57], v[150:153], v[166:169], v[54:57]
	v_mfma_f32_16x16x32_bf16 v[50:53], v[158:161], v[166:169], v[50:53]
	v_mfma_f32_16x16x32_bf16 v[38:41], v[150:153], v[206:209], v[38:41]
	v_mfma_f32_16x16x32_bf16 v[34:37], v[158:161], v[206:209], v[34:37]
	v_mfma_f32_16x16x32_bf16 v[22:25], v[150:153], v[234:237], v[22:25]
	v_mfma_f32_16x16x32_bf16 v[18:21], v[158:161], v[234:237], v[18:21]
	v_mfma_f32_16x16x32_bf16 v[6:9], v[150:153], v[242:245], v[6:9]
	v_mfma_f32_16x16x32_bf16 v[2:5], v[158:161], v[242:245], v[2:5]
	s_setprio 0
	s_barrier
	s_add_i32 s93, 0, 0x18000
	v_add_u32_e32 v0, s93, v171
	s_add_i32 vcc_lo, 0, 0x1c000
	ds_read_b128 v[130:133], v0
	ds_read_b128 v[134:137], v0 offset:1024
	ds_read_b128 v[138:141], v0 offset:2048
	ds_read_b128 v[142:145], v0 offset:3072
	v_add_u32_e32 v0, vcc_lo, v171
	ds_read_b128 v[146:149], v0
	ds_read_b128 v[150:153], v0 offset:1024
	ds_read_b128 v[154:157], v0 offset:2048
	ds_read_b128 v[158:161], v0 offset:3072
	s_add_u32 s4, s94, 0x2000
	s_addc_u32 s5, s95, 0
	s_mov_b32 m0, s20
	v_lshl_add_u64 v[214:215], s[4:5], 0, v[186:187]
	ds_read_b128 v[162:165], v203 offset:32768
	ds_read_b128 v[166:169], v203 offset:33792
	ds_read_b128 v[194:197], v203 offset:34816
	ds_read_b128 v[206:209], v203 offset:35840
	ds_read_b128 v[230:233], v203 offset:36864
	ds_read_b128 v[234:237], v203 offset:37888
	ds_read_b128 v[238:241], v203 offset:38912
	ds_read_b128 v[242:245], v203 offset:39936
	global_load_lds_dwordx4 v[214:215], off
	v_lshl_add_u64 v[214:215], s[4:5], 0, v[182:183]
	s_mov_b32 m0, s21
	s_nop 0
	global_load_lds_dwordx4 v[214:215], off
	s_waitcnt vmcnt(8)
	s_waitcnt lgkmcnt(0)
	s_barrier
	s_setprio 1
	s_waitcnt lgkmcnt(0)
	v_mfma_f32_16x16x32_bf16 v[126:129], v[130:133], v[162:165], v[126:129]
	v_mfma_f32_16x16x32_bf16 v[122:125], v[138:141], v[162:165], v[122:125]
	v_mfma_f32_16x16x32_bf16 v[110:113], v[130:133], v[194:197], v[110:113]
	v_mfma_f32_16x16x32_bf16 v[106:109], v[138:141], v[194:197], v[106:109]
	v_mfma_f32_16x16x32_bf16 v[94:97], v[130:133], v[230:233], v[94:97]
	v_mfma_f32_16x16x32_bf16 v[90:93], v[138:141], v[230:233], v[90:93]
	v_mfma_f32_16x16x32_bf16 v[78:81], v[130:133], v[238:241], v[78:81]
	v_mfma_f32_16x16x32_bf16 v[74:77], v[138:141], v[238:241], v[74:77]
	v_mfma_f32_16x16x32_bf16 v[126:129], v[134:137], v[166:169], v[126:129]
	v_mfma_f32_16x16x32_bf16 v[122:125], v[142:145], v[166:169], v[122:125]
	v_mfma_f32_16x16x32_bf16 v[110:113], v[134:137], v[206:209], v[110:113]
	v_mfma_f32_16x16x32_bf16 v[106:109], v[142:145], v[206:209], v[106:109]
	v_mfma_f32_16x16x32_bf16 v[94:97], v[134:137], v[234:237], v[94:97]
	v_mfma_f32_16x16x32_bf16 v[90:93], v[142:145], v[234:237], v[90:93]
	v_mfma_f32_16x16x32_bf16 v[78:81], v[134:137], v[242:245], v[78:81]
	v_mfma_f32_16x16x32_bf16 v[74:77], v[142:145], v[242:245], v[74:77]
	s_setprio 0
	s_setprio 1
	v_mfma_f32_16x16x32_bf16 v[118:121], v[146:149], v[162:165], v[118:121]
	v_mfma_f32_16x16x32_bf16 v[114:117], v[154:157], v[162:165], v[114:117]
	v_mfma_f32_16x16x32_bf16 v[102:105], v[146:149], v[194:197], v[102:105]
	v_mfma_f32_16x16x32_bf16 v[98:101], v[154:157], v[194:197], v[98:101]
	v_mfma_f32_16x16x32_bf16 v[86:89], v[146:149], v[230:233], v[86:89]
	v_mfma_f32_16x16x32_bf16 v[82:85], v[154:157], v[230:233], v[82:85]
	v_mfma_f32_16x16x32_bf16 v[70:73], v[146:149], v[238:241], v[70:73]
	v_mfma_f32_16x16x32_bf16 v[66:69], v[154:157], v[238:241], v[66:69]
	v_mfma_f32_16x16x32_bf16 v[118:121], v[150:153], v[166:169], v[118:121]
	v_mfma_f32_16x16x32_bf16 v[114:117], v[158:161], v[166:169], v[114:117]
	v_mfma_f32_16x16x32_bf16 v[102:105], v[150:153], v[206:209], v[102:105]
	v_mfma_f32_16x16x32_bf16 v[98:101], v[158:161], v[206:209], v[98:101]
	v_mfma_f32_16x16x32_bf16 v[86:89], v[150:153], v[234:237], v[86:89]
	v_mfma_f32_16x16x32_bf16 v[82:85], v[158:161], v[234:237], v[82:85]
	v_mfma_f32_16x16x32_bf16 v[70:73], v[150:153], v[242:245], v[70:73]
	v_mfma_f32_16x16x32_bf16 v[66:69], v[158:161], v[242:245], v[66:69]
	s_setprio 0
	s_barrier
; #define PG8_STAGE(bufoff, gbase, voff) do { _Pragma("unroll") for (int _i = 0; _i < 2; ++_i) \
;         __builtin_amdgcn_global_load_lds((const unsigned*)((const char*)(gbase) + (voff)[_i]), (LAS unsigned*)(lds + (bufoff) + ldsw + _i * 8192), 16, 0, 0); } while (0)
; #define PG8_LDA(dst, b, h) do { _Pragma("unroll") for (int m = 0; m < 4; ++m) _Pragma("unroll") for (int k = 0; k < 2; ++k) dst[m][k] = *(const LAS bf16x8*)(lds + PG8_SA(b, h) + aoff + m * 2048 + k * 1024); } while (0)
; #define PG8_LDB(dst, b, h) do { _Pragma("unroll") for (int n = 0; n < 2; ++n) _Pragma("unroll") for (int k = 0; k < 2; ++k) dst[n][k] = *(const LAS bf16x8*)(lds + PG8_SB(b, h) + boff + n * 2048 + k * 1024); } while (0)
; #define PG8_WAIT_V(n) asm volatile("s_waitcnt vmcnt(" #n ")" ::: "memory")
; template <bool ALIGN_EPI, class Epi, class Sched>
; DEV void gemm_phase(LAS unsigned char* lds, const Gemm g, const Sched& S, const Epi& E) {
;     ...
;         for (int t = 0; t < nt; t += 2) {
;             const bool last = (t == nt - 2);
;             const char* a1 = cA + (size_t)(t + 1) * kstep;
;             const char* a2 = last ? nA : cA + (size_t)(t + 2) * kstep; const char* b2 = last ? nB : cB + (size_t)(t + 2) * kstep;
;             const char* a3 = a2 + kstep; const char* b3 = b2 + kstep;
;             PG8_LDB(B0, 0, 0); PG8_LDB(B1, 0, 1); PG8_SCHED; PG8_LDA(At, 0, 0); PG8_STAGE(PG8_SA(1, 1), a1 + hstepA, voffA);
;             PG8_WAIT_V(8); PG8_WAIT_L(0); PG8_BAR; PG8_MMA(0, 0, At, B0); PG8_MMA(0, 1, At, B1); PG8_BAR; PG8_SCHED;
;             PG8_LDA(At, 0, 1); PG8_STAGE(PG8_SB(0, 0), b2, voffB); PG8_STAGE(PG8_SB(0, 1), b2 + hstep, voffB); PG8_STAGE(PG8_SA(0, 0), a2, voffA);
;             PG8_WAIT_V(8); PG8_WAIT_L(0); PG8_BAR; PG8_MMA(1, 0, At, B0); PG8_MMA(1, 1, At, B1); PG8_BAR; PG8_SCHED;
;             PG8_LDB(B0, 1, 0); PG8_LDB(B1, 1, 1); PG8_SCHED; PG8_LDA(At, 1, 0); PG8_STAGE(PG8_SA(0, 1), a2 + hstepA, voffA);
;             PG8_WAIT_V(8); PG8_WAIT_L(0); PG8_BAR; PG8_MMA(0, 0, At, B0); PG8_MMA(0, 1, At, B1); PG8_BAR; PG8_SCHED;
;             PG8_LDA(At, 1, 1); PG8_STAGE(PG8_SB(1, 0), b3, voffB); PG8_STAGE(PG8_SB(1, 1), b3 + hstep, voffB); PG8_STAGE(PG8_SA(1, 0), a3, voffA);
;             PG8_WAIT_V(8); PG8_WAIT_L(0); PG8_BAR; PG8_MMA(1, 0, At, B0); PG8_MMA(1, 1, At, B1); PG8_BAR; PG8_SCHED;
;         }
;         if (ALIGN_EPI) { if (wr == 0) PG8_BAR; }
	s_add_i32 s4, s93, s12
	v_lshl_add_u64 v[214:215], v[246:247], 0, s[30:31]
	s_mov_b32 m0, s4
	ds_read_b128 v[162:165], v203 offset:49152
	ds_read_b128 v[166:169], v203 offset:50176
	ds_read_b128 v[194:197], v203 offset:51200
	ds_read_b128 v[206:209], v203 offset:52224
	ds_read_b128 v[230:233], v203 offset:53248
	ds_read_b128 v[234:237], v203 offset:54272
	ds_read_b128 v[238:241], v203 offset:55296
	ds_read_b128 v[242:245], v203 offset:56320
	global_load_lds_dwordx4 v[214:215], off
	s_add_i32 m0, s4, 0x2000
	s_add_u32 s4, s46, 0x40080
	v_lshl_add_u64 v[214:215], v[248:249], 0, s[30:31]
	s_addc_u32 s5, s47, 0
	s_add_i32 s46, vcc_lo, s12
	global_load_lds_dwordx4 v[214:215], off
	v_lshl_add_u64 v[214:215], s[4:5], 0, v[184:185]
	s_mov_b32 m0, s46
	s_nop 0
	global_load_lds_dwordx4 v[214:215], off
	v_lshl_add_u64 v[214:215], s[4:5], 0, v[180:181]
	s_add_i32 m0, s46, 0x2000
	s_nop 0
	global_load_lds_dwordx4 v[214:215], off
	v_lshl_add_u64 v[214:215], v[250:251], 0, s[30:31]
	s_mov_b32 m0, s78
	s_nop 0
	global_load_lds_dwordx4 v[214:215], off
	v_lshl_add_u64 v[214:215], v[228:229], 0, s[30:31]
	s_mov_b32 m0, s79
	s_nop 0
	global_load_lds_dwordx4 v[214:215], off
	s_waitcnt vmcnt(8)
	s_waitcnt lgkmcnt(0)
	s_barrier
	s_setprio 1
	s_waitcnt lgkmcnt(0)
	v_mfma_f32_16x16x32_bf16 v[62:65], v[130:133], v[162:165], v[62:65]
	v_mfma_f32_16x16x32_bf16 v[58:61], v[138:141], v[162:165], v[58:61]
	v_mfma_f32_16x16x32_bf16 v[46:49], v[130:133], v[194:197], v[46:49]
	v_mfma_f32_16x16x32_bf16 v[42:45], v[138:141], v[194:197], v[42:45]
	v_mfma_f32_16x16x32_bf16 v[30:33], v[130:133], v[230:233], v[30:33]
	v_mfma_f32_16x16x32_bf16 v[26:29], v[138:141], v[230:233], v[26:29]
	v_mfma_f32_16x16x32_bf16 v[14:17], v[130:133], v[238:241], v[14:17]
	v_mfma_f32_16x16x32_bf16 v[10:13], v[138:141], v[238:241], v[10:13]
	v_mfma_f32_16x16x32_bf16 v[62:65], v[134:137], v[166:169], v[62:65]
	v_mfma_f32_16x16x32_bf16 v[58:61], v[142:145], v[166:169], v[58:61]
	v_mfma_f32_16x16x32_bf16 v[46:49], v[134:137], v[206:209], v[46:49]
	v_mfma_f32_16x16x32_bf16 v[42:45], v[142:145], v[206:209], v[42:45]
	v_mfma_f32_16x16x32_bf16 v[30:33], v[134:137], v[234:237], v[30:33]
	v_mfma_f32_16x16x32_bf16 v[26:29], v[142:145], v[234:237], v[26:29]
	v_mfma_f32_16x16x32_bf16 v[14:17], v[134:137], v[242:245], v[14:17]
	v_mfma_f32_16x16x32_bf16 v[10:13], v[142:145], v[242:245], v[10:13]
	s_setprio 0
	s_setprio 1
	v_mfma_f32_16x16x32_bf16 v[54:57], v[146:149], v[162:165], v[54:57]
	v_mfma_f32_16x16x32_bf16 v[50:53], v[154:157], v[162:165], v[50:53]
	v_mfma_f32_16x16x32_bf16 v[38:41], v[146:149], v[194:197], v[38:41]
	v_mfma_f32_16x16x32_bf16 v[34:37], v[154:157], v[194:197], v[34:37]
	v_mfma_f32_16x16x32_bf16 v[22:25], v[146:149], v[230:233], v[22:25]
	v_mfma_f32_16x16x32_bf16 v[18:21], v[154:157], v[230:233], v[18:21]
	v_mfma_f32_16x16x32_bf16 v[6:9], v[146:149], v[238:241], v[6:9]
	v_mfma_f32_16x16x32_bf16 v[2:5], v[154:157], v[238:241], v[2:5]
	v_mfma_f32_16x16x32_bf16 v[54:57], v[150:153], v[166:169], v[54:57]
	v_mfma_f32_16x16x32_bf16 v[50:53], v[158:161], v[166:169], v[50:53]
	v_mfma_f32_16x16x32_bf16 v[38:41], v[150:153], v[206:209], v[38:41]
	v_mfma_f32_16x16x32_bf16 v[34:37], v[158:161], v[206:209], v[34:37]
	v_mfma_f32_16x16x32_bf16 v[22:25], v[150:153], v[234:237], v[22:25]
	v_mfma_f32_16x16x32_bf16 v[18:21], v[158:161], v[234:237], v[18:21]
	v_mfma_f32_16x16x32_bf16 v[6:9], v[150:153], v[242:245], v[6:9]
	v_mfma_f32_16x16x32_bf16 v[2:5], v[158:161], v[242:245], v[2:5]
	s_setprio 0
	s_add_i32 s87, s87, 2
	s_add_u32 s70, s70, 0x100
	s_addc_u32 s85, s85, 0
	s_cmp_gt_u32 s87, 13
	s_mov_b64 s[4:5], s[6:7]
	s_cbranch_scc1 .Lkx_315
	s_add_u32 s6, s4, 0x100
	s_addc_u32 s7, s5, 0
	s_add_i32 s93, 0, 0x10000
	s_cmp_eq_u32 s87, 12
	s_cselect_b32 s95, s17, s7
	s_cselect_b32 s94, s36, s6
	v_add_u32_e32 v0, s93, v171
	s_cselect_b32 s47, s41, s85
	s_cselect_b32 s46, s64, s70
	s_add_i32 vcc_lo, 0, 0x14000
	s_barrier
	s_branch .Lkr_315
.Lkx_315:
	s_barrier
	s_and_b64 vcc, exec, s[54:55]
	s_cbranch_vccz .LBB0_318
	s_barrier

; #define PG8_STAGE(bufoff, gbase, voff) do { _Pragma("unroll") for (int _i = 0; _i < 2; ++_i) \
;         __builtin_amdgcn_global_load_lds((const unsigned*)((const char*)(gbase) + (voff)[_i]), (LAS unsigned*)(lds + (bufoff) + ldsw + _i * 8192), 16, 0, 0); } while (0)
; #define PG8_LDA(dst, b, h) do { _Pragma("unroll") for (int m = 0; m < 4; ++m) _Pragma("unroll") for (int k = 0; k < 2; ++k) dst[m][k] = *(const LAS bf16x8*)(lds + PG8_SA(b, h) + aoff + m * 2048 + k * 1024); } while (0)
; #define PG8_LDB(dst, b, h) do { _Pragma("unroll") for (int n = 0; n < 2; ++n) _Pragma("unroll") for (int k = 0; k < 2; ++k) dst[n][k] = *(const LAS bf16x8*)(lds + PG8_SB(b, h) + boff + n * 2048 + k * 1024); } while (0)
; #define PG8_MMA(ai, bj, At, Bt) do { __builtin_amdgcn_s_setprio(1); _Pragma("unroll") for (int m = 0; m < 4; ++m) _Pragma("unroll") for (int n = 0; n < 2; ++n) _Pragma("unroll") for (int k = 0; k < 2; ++k) \
;         acc[ai][bj][m][n] = __builtin_amdgcn_mfma_f32_16x16x32_bf16(Bt[n][k], At[m][k], acc[ai][bj][m][n], 0, 0, 0); __builtin_amdgcn_s_setprio(0); } while (0)
; #define PG8_WAIT_V(n) asm volatile("s_waitcnt vmcnt(" #n ")" ::: "memory")
; #define PG8_WAIT_L(n) asm volatile("s_waitcnt lgkmcnt(" #n ")" ::: "memory")
; #define PG8_BAR __builtin_amdgcn_s_barrier()
; #define PG8_SCHED __builtin_amdgcn_sched_barrier(0)
; template <bool ALIGN_EPI, class Epi, class Sched>
; DEV void gemm_phase(LAS unsigned char* lds, const Gemm g, const Sched& S, const Epi& E) {
;     ...
;             PG8_LDB(B0, 0, 0); PG8_LDB(B1, 0, 1); PG8_SCHED; PG8_LDA(At, 0, 0); PG8_STAGE(PG8_SA(1, 1), a1 + hstepA, voffA);
;             PG8_WAIT_V(8); PG8_WAIT_L(0); PG8_BAR; PG8_MMA(0, 0, At, B0); PG8_MMA(0, 1, At, B1); PG8_BAR; PG8_SCHED;
;             PG8_LDA(At, 0, 1); PG8_STAGE(PG8_SB(0, 0), b2, voffB); PG8_STAGE(PG8_SB(0, 1), b2 + hstep, voffB); PG8_STAGE(PG8_SA(0, 0), a2, voffA);
;             PG8_WAIT_V(8); PG8_WAIT_L(0); PG8_BAR; PG8_MMA(1, 0, At, B0); PG8_MMA(1, 1, At, B1); PG8_BAR; PG8_SCHED;
.Lkr_488:
	ds_read_b128 v[130:133], v142
	ds_read_b128 v[134:137], v142 offset:1024
	ds_read_b128 v[138:141], v142 offset:2048
	ds_read_b128 v[142:145], v142 offset:3072
	ds_read_b128 v[146:149], v168
	ds_read_b128 v[150:153], v168 offset:1024
	ds_read_b128 v[164:167], v168 offset:2048
	ds_read_b128 v[180:183], v168 offset:3072
	v_lshl_add_u64 v[168:169], s[4:5], 0, v[160:161]
	s_add_i32 m0, s15, 0xc000
	ds_read_b128 v[190:193], v188
	ds_read_b128 v[194:197], v188 offset:1024
	ds_read_b128 v[198:201], v188 offset:2048
	ds_read_b128 v[202:205], v188 offset:3072
	ds_read_b128 v[206:209], v188 offset:4096
	ds_read_b128 v[230:233], v188 offset:5120
	ds_read_b128 v[234:237], v188 offset:6144
	ds_read_b128 v[238:241], v188 offset:7168
	global_load_lds_dwordx4 v[168:169], off
	v_lshl_add_u64 v[168:169], s[4:5], 0, v[162:163]
	s_add_i32 m0, s15, 0xe000
	s_nop 0
	global_load_lds_dwordx4 v[168:169], off
	s_waitcnt vmcnt(8)
	s_waitcnt lgkmcnt(0)
	s_barrier
	s_setprio 1
	s_waitcnt lgkmcnt(0)
	v_mfma_f32_16x16x32_bf16 v[126:129], v[130:133], v[190:193], v[126:129]
	v_mfma_f32_16x16x32_bf16 v[122:125], v[138:141], v[190:193], v[122:125]
	v_mfma_f32_16x16x32_bf16 v[110:113], v[130:133], v[198:201], v[110:113]
	v_mfma_f32_16x16x32_bf16 v[106:109], v[138:141], v[198:201], v[106:109]
	v_mfma_f32_16x16x32_bf16 v[98:101], v[130:133], v[206:209], v[98:101]
	v_mfma_f32_16x16x32_bf16 v[90:93], v[138:141], v[206:209], v[90:93]
	v_mfma_f32_16x16x32_bf16 v[82:85], v[130:133], v[234:237], v[82:85]
	v_mfma_f32_16x16x32_bf16 v[74:77], v[138:141], v[234:237], v[74:77]
	v_mfma_f32_16x16x32_bf16 v[126:129], v[134:137], v[194:197], v[126:129]
	v_mfma_f32_16x16x32_bf16 v[122:125], v[142:145], v[194:197], v[122:125]
	v_mfma_f32_16x16x32_bf16 v[110:113], v[134:137], v[202:205], v[110:113]
	v_mfma_f32_16x16x32_bf16 v[106:109], v[142:145], v[202:205], v[106:109]
	v_mfma_f32_16x16x32_bf16 v[98:101], v[134:137], v[230:233], v[98:101]
	v_mfma_f32_16x16x32_bf16 v[90:93], v[142:145], v[230:233], v[90:93]
	v_mfma_f32_16x16x32_bf16 v[82:85], v[134:137], v[238:241], v[82:85]
	v_mfma_f32_16x16x32_bf16 v[74:77], v[142:145], v[238:241], v[74:77]
	s_setprio 0
	s_setprio 1
	v_mfma_f32_16x16x32_bf16 v[118:121], v[146:149], v[190:193], v[118:121]
	v_mfma_f32_16x16x32_bf16 v[114:117], v[164:167], v[190:193], v[114:117]
	v_mfma_f32_16x16x32_bf16 v[102:105], v[146:149], v[198:201], v[102:105]
	v_mfma_f32_16x16x32_bf16 v[94:97], v[164:167], v[198:201], v[94:97]
	v_mfma_f32_16x16x32_bf16 v[86:89], v[146:149], v[206:209], v[86:89]
	v_mfma_f32_16x16x32_bf16 v[78:81], v[164:167], v[206:209], v[78:81]
	v_mfma_f32_16x16x32_bf16 v[70:73], v[146:149], v[234:237], v[70:73]
	v_mfma_f32_16x16x32_bf16 v[66:69], v[164:167], v[234:237], v[66:69]
	v_mfma_f32_16x16x32_bf16 v[118:121], v[150:153], v[194:197], v[118:121]
	v_mfma_f32_16x16x32_bf16 v[114:117], v[180:183], v[194:197], v[114:117]
	v_mfma_f32_16x16x32_bf16 v[102:105], v[150:153], v[202:205], v[102:105]
	v_mfma_f32_16x16x32_bf16 v[94:97], v[180:183], v[202:205], v[94:97]
	v_mfma_f32_16x16x32_bf16 v[86:89], v[150:153], v[230:233], v[86:89]
	v_mfma_f32_16x16x32_bf16 v[78:81], v[180:183], v[230:233], v[78:81]
	v_mfma_f32_16x16x32_bf16 v[70:73], v[150:153], v[238:241], v[70:73]
	v_mfma_f32_16x16x32_bf16 v[66:69], v[180:183], v[238:241], v[66:69]
	s_setprio 0
	s_barrier
	s_add_i32 s4, s24, s13
	v_lshl_add_u64 v[168:169], s[50:51], 0, v[0:1]
	s_mov_b32 m0, s4
	ds_read_b128 v[190:193], v188 offset:16384
	ds_read_b128 v[194:197], v188 offset:17408
	ds_read_b128 v[198:201], v188 offset:18432
	ds_read_b128 v[202:205], v188 offset:19456
	ds_read_b128 v[206:209], v188 offset:20480
	ds_read_b128 v[230:233], v188 offset:21504
	ds_read_b128 v[234:237], v188 offset:22528
	ds_read_b128 v[238:241], v188 offset:23552
	global_load_lds_dwordx4 v[168:169], off
	s_add_i32 m0, s4, 0x2000
	s_add_u32 s4, s50, 0xc0000
	v_lshl_add_u64 v[184:185], s[50:51], 0, v[154:155]
	s_addc_u32 s5, s51, 0
	s_add_i32 s24, s25, s13
	global_load_lds_dwordx4 v[184:185], off
	v_lshl_add_u64 v[214:215], s[4:5], 0, v[0:1]
	s_mov_b32 m0, s24
	v_lshl_add_u64 v[228:229], s[52:53], 0, v[156:157]
	global_load_lds_dwordx4 v[214:215], off
	v_lshl_add_u64 v[214:215], s[4:5], 0, v[154:155]
	s_add_i32 m0, s24, 0x2000
	s_nop 0
	global_load_lds_dwordx4 v[214:215], off
	v_lshl_add_u64 v[214:215], s[52:53], 0, v[158:159]
	s_mov_b32 m0, s15
	s_nop 0
	global_load_lds_dwordx4 v[214:215], off
	s_mov_b32 m0, s17
	s_nop 0
	global_load_lds_dwordx4 v[228:229], off
	s_waitcnt vmcnt(8)
	s_waitcnt lgkmcnt(0)
	s_barrier
; #define PG8_STAGE(bufoff, gbase, voff) do { _Pragma("unroll") for (int _i = 0; _i < 2; ++_i) \
;         __builtin_amdgcn_global_load_lds((const unsigned*)((const char*)(gbase) + (voff)[_i]), (LAS unsigned*)(lds + (bufoff) + ldsw + _i * 8192), 16, 0, 0); } while (0)
; #define PG8_LDA(dst, b, h) do { _Pragma("unroll") for (int m = 0; m < 4; ++m) _Pragma("unroll") for (int k = 0; k < 2; ++k) dst[m][k] = *(const LAS bf16x8*)(lds + PG8_SA(b, h) + aoff + m * 2048 + k * 1024); } while (0)
; #define PG8_LDB(dst, b, h) do { _Pragma("unroll") for (int n = 0; n < 2; ++n) _Pragma("unroll") for (int k = 0; k < 2; ++k) dst[n][k] = *(const LAS bf16x8*)(lds + PG8_SB(b, h) + boff + n * 2048 + k * 1024); } while (0)
; #define PG8_MMA(ai, bj, At, Bt) do { __builtin_amdgcn_s_setprio(1); _Pragma("unroll") for (int m = 0; m < 4; ++m) _Pragma("unroll") for (int n = 0; n < 2; ++n) _Pragma("unroll") for (int k = 0; k < 2; ++k) \
;         acc[ai][bj][m][n] = __builtin_amdgcn_mfma_f32_16x16x32_bf16(Bt[n][k], At[m][k], acc[ai][bj][m][n], 0, 0, 0); __builtin_amdgcn_s_setprio(0); } while (0)
; #define PG8_WAIT_V(n) asm volatile("s_waitcnt vmcnt(" #n ")" ::: "memory")
; #define PG8_WAIT_L(n) asm volatile("s_waitcnt lgkmcnt(" #n ")" ::: "memory")
; #define PG8_BAR __builtin_amdgcn_s_barrier()
; #define PG8_SCHED __builtin_amdgcn_sched_barrier(0)
; template <bool ALIGN_EPI, class Epi, class Sched>
; DEV void gemm_phase(LAS unsigned char* lds, const Gemm g, const Sched& S, const Epi& E) {
;     ...
;             PG8_WAIT_V(8); PG8_WAIT_L(0); PG8_BAR; PG8_MMA(1, 0, At, B0); PG8_MMA(1, 1, At, B1); PG8_BAR; PG8_SCHED;
;             PG8_LDB(B0, 1, 0); PG8_LDB(B1, 1, 1); PG8_SCHED; PG8_LDA(At, 1, 0); PG8_STAGE(PG8_SA(0, 1), a2 + hstepA, voffA);
;             PG8_WAIT_V(8); PG8_WAIT_L(0); PG8_BAR; PG8_MMA(0, 0, At, B0); PG8_MMA(0, 1, At, B1); PG8_BAR; PG8_SCHED;
	s_setprio 1
	s_waitcnt lgkmcnt(0)
	v_mfma_f32_16x16x32_bf16 v[62:65], v[130:133], v[190:193], v[62:65]
	v_mfma_f32_16x16x32_bf16 v[58:61], v[138:141], v[190:193], v[58:61]
	v_mfma_f32_16x16x32_bf16 v[50:53], v[130:133], v[198:201], v[50:53]
	v_mfma_f32_16x16x32_bf16 v[42:45], v[138:141], v[198:201], v[42:45]
	v_mfma_f32_16x16x32_bf16 v[34:37], v[130:133], v[206:209], v[34:37]
	v_mfma_f32_16x16x32_bf16 v[26:29], v[138:141], v[206:209], v[26:29]
	v_mfma_f32_16x16x32_bf16 v[18:21], v[130:133], v[234:237], v[18:21]
	v_mfma_f32_16x16x32_bf16 v[10:13], v[138:141], v[234:237], v[10:13]
	v_mfma_f32_16x16x32_bf16 v[62:65], v[134:137], v[194:197], v[62:65]
	v_mfma_f32_16x16x32_bf16 v[58:61], v[142:145], v[194:197], v[58:61]
	v_mfma_f32_16x16x32_bf16 v[50:53], v[134:137], v[202:205], v[50:53]
	v_mfma_f32_16x16x32_bf16 v[42:45], v[142:145], v[202:205], v[42:45]
	v_mfma_f32_16x16x32_bf16 v[34:37], v[134:137], v[230:233], v[34:37]
	v_mfma_f32_16x16x32_bf16 v[26:29], v[142:145], v[230:233], v[26:29]
	v_mfma_f32_16x16x32_bf16 v[18:21], v[134:137], v[238:241], v[18:21]
	v_mfma_f32_16x16x32_bf16 v[10:13], v[142:145], v[238:241], v[10:13]
	s_setprio 0
	s_setprio 1
	v_mfma_f32_16x16x32_bf16 v[54:57], v[146:149], v[190:193], v[54:57]
	v_mfma_f32_16x16x32_bf16 v[46:49], v[164:167], v[190:193], v[46:49]
	v_mfma_f32_16x16x32_bf16 v[38:41], v[146:149], v[198:201], v[38:41]
	v_mfma_f32_16x16x32_bf16 v[30:33], v[164:167], v[198:201], v[30:33]
	v_mfma_f32_16x16x32_bf16 v[22:25], v[146:149], v[206:209], v[22:25]
	v_mfma_f32_16x16x32_bf16 v[14:17], v[164:167], v[206:209], v[14:17]
	v_mfma_f32_16x16x32_bf16 v[6:9], v[146:149], v[234:237], v[6:9]
	v_mfma_f32_16x16x32_bf16 v[2:5], v[164:167], v[234:237], v[2:5]
	v_mfma_f32_16x16x32_bf16 v[54:57], v[150:153], v[194:197], v[54:57]
	v_mfma_f32_16x16x32_bf16 v[46:49], v[180:183], v[194:197], v[46:49]
	v_mfma_f32_16x16x32_bf16 v[38:41], v[150:153], v[202:205], v[38:41]
	v_mfma_f32_16x16x32_bf16 v[30:33], v[180:183], v[202:205], v[30:33]
	v_mfma_f32_16x16x32_bf16 v[22:25], v[150:153], v[230:233], v[22:25]
	v_mfma_f32_16x16x32_bf16 v[14:17], v[180:183], v[230:233], v[14:17]
	v_mfma_f32_16x16x32_bf16 v[6:9], v[150:153], v[238:241], v[6:9]
	v_mfma_f32_16x16x32_bf16 v[2:5], v[180:183], v[238:241], v[2:5]
	s_setprio 0
	s_barrier
	s_add_i32 s24, 0, 0x18000
	s_add_i32 s25, 0, 0x1c000
	v_add_u32_e32 v142, s24, v186
	v_add_u32_e32 v180, s25, v186
	ds_read_b128 v[130:133], v142
	ds_read_b128 v[134:137], v142 offset:1024
	ds_read_b128 v[138:141], v142 offset:2048
	ds_read_b128 v[142:145], v142 offset:3072
	ds_read_b128 v[146:149], v180
	ds_read_b128 v[150:153], v180 offset:1024
	ds_read_b128 v[164:167], v180 offset:2048
	ds_read_b128 v[180:183], v180 offset:3072
	s_add_u32 s4, s52, 0xc0000
	s_addc_u32 s5, s53, 0
	s_mov_b32 m0, s20
	v_lshl_add_u64 v[242:243], s[4:5], 0, v[158:159]
	ds_read_b128 v[190:193], v188 offset:32768
	ds_read_b128 v[194:197], v188 offset:33792
	ds_read_b128 v[198:201], v188 offset:34816
	ds_read_b128 v[202:205], v188 offset:35840
	ds_read_b128 v[206:209], v188 offset:36864
	ds_read_b128 v[230:233], v188 offset:37888
	ds_read_b128 v[234:237], v188 offset:38912
	ds_read_b128 v[238:241], v188 offset:39936
	global_load_lds_dwordx4 v[242:243], off
	v_lshl_add_u64 v[242:243], s[4:5], 0, v[156:157]
	s_mov_b32 m0, s21
	s_nop 0
	global_load_lds_dwordx4 v[242:243], off
	s_waitcnt vmcnt(8)
	s_waitcnt lgkmcnt(0)
	s_barrier
	s_setprio 1
	s_waitcnt lgkmcnt(0)
	v_mfma_f32_16x16x32_bf16 v[126:129], v[130:133], v[190:193], v[126:129]
	v_mfma_f32_16x16x32_bf16 v[122:125], v[138:141], v[190:193], v[122:125]
	v_mfma_f32_16x16x32_bf16 v[110:113], v[130:133], v[198:201], v[110:113]
	v_mfma_f32_16x16x32_bf16 v[106:109], v[138:141], v[198:201], v[106:109]
	v_mfma_f32_16x16x32_bf16 v[98:101], v[130:133], v[206:209], v[98:101]
	v_mfma_f32_16x16x32_bf16 v[90:93], v[138:141], v[206:209], v[90:93]
	v_mfma_f32_16x16x32_bf16 v[82:85], v[130:133], v[234:237], v[82:85]
	v_mfma_f32_16x16x32_bf16 v[74:77], v[138:141], v[234:237], v[74:77]
	v_mfma_f32_16x16x32_bf16 v[126:129], v[134:137], v[194:197], v[126:129]
	v_mfma_f32_16x16x32_bf16 v[122:125], v[142:145], v[194:197], v[122:125]
	v_mfma_f32_16x16x32_bf16 v[110:113], v[134:137], v[202:205], v[110:113]
	v_mfma_f32_16x16x32_bf16 v[106:109], v[142:145], v[202:205], v[106:109]
	v_mfma_f32_16x16x32_bf16 v[98:101], v[134:137], v[230:233], v[98:101]
	v_mfma_f32_16x16x32_bf16 v[90:93], v[142:145], v[230:233], v[90:93]
	v_mfma_f32_16x16x32_bf16 v[82:85], v[134:137], v[238:241], v[82:85]
	v_mfma_f32_16x16x32_bf16 v[74:77], v[142:145], v[238:241], v[74:77]
	s_setprio 0
	s_setprio 1
	v_mfma_f32_16x16x32_bf16 v[118:121], v[146:149], v[190:193], v[118:121]
	v_mfma_f32_16x16x32_bf16 v[114:117], v[164:167], v[190:193], v[114:117]
	v_mfma_f32_16x16x32_bf16 v[102:105], v[146:149], v[198:201], v[102:105]
	v_mfma_f32_16x16x32_bf16 v[94:97], v[164:167], v[198:201], v[94:97]
	v_mfma_f32_16x16x32_bf16 v[86:89], v[146:149], v[206:209], v[86:89]
	v_mfma_f32_16x16x32_bf16 v[78:81], v[164:167], v[206:209], v[78:81]
	v_mfma_f32_16x16x32_bf16 v[70:73], v[146:149], v[234:237], v[70:73]
	v_mfma_f32_16x16x32_bf16 v[66:69], v[164:167], v[234:237], v[66:69]
	v_mfma_f32_16x16x32_bf16 v[118:121], v[150:153], v[194:197], v[118:121]
	v_mfma_f32_16x16x32_bf16 v[114:117], v[180:183], v[194:197], v[114:117]
	v_mfma_f32_16x16x32_bf16 v[102:105], v[150:153], v[202:205], v[102:105]
	v_mfma_f32_16x16x32_bf16 v[94:97], v[180:183], v[202:205], v[94:97]
	v_mfma_f32_16x16x32_bf16 v[86:89], v[150:153], v[230:233], v[86:89]
	v_mfma_f32_16x16x32_bf16 v[78:81], v[180:183], v[230:233], v[78:81]
	v_mfma_f32_16x16x32_bf16 v[70:73], v[150:153], v[238:241], v[70:73]
	v_mfma_f32_16x16x32_bf16 v[66:69], v[180:183], v[238:241], v[66:69]
	s_setprio 0
	s_barrier
; #define PG8_STAGE(bufoff, gbase, voff) do { _Pragma("unroll") for (int _i = 0; _i < 2; ++_i) \
;         __builtin_amdgcn_global_load_lds((const unsigned*)((const char*)(gbase) + (voff)[_i]), (LAS unsigned*)(lds + (bufoff) + ldsw + _i * 8192), 16, 0, 0); } while (0)
; #define PG8_LDA(dst, b, h) do { _Pragma("unroll") for (int m = 0; m < 4; ++m) _Pragma("unroll") for (int k = 0; k < 2; ++k) dst[m][k] = *(const LAS bf16x8*)(lds + PG8_SA(b, h) + aoff + m * 2048 + k * 1024); } while (0)
; #define PG8_LDB(dst, b, h) do { _Pragma("unroll") for (int n = 0; n < 2; ++n) _Pragma("unroll") for (int k = 0; k < 2; ++k) dst[n][k] = *(const LAS bf16x8*)(lds + PG8_SB(b, h) + boff + n * 2048 + k * 1024); } while (0)
; #define PG8_WAIT_V(n) asm volatile("s_waitcnt vmcnt(" #n ")" ::: "memory")
; template <bool ALIGN_EPI, class Epi, class Sched>
; DEV void gemm_phase(LAS unsigned char* lds, const Gemm g, const Sched& S, const Epi& E) {
;     ...
;         for (int t = 0; t < nt; t += 2) {
;             const bool last = (t == nt - 2);
;             const char* a1 = cA + (size_t)(t + 1) * kstep;
;             const char* a2 = last ? nA : cA + (size_t)(t + 2) * kstep; const char* b2 = last ? nB : cB + (size_t)(t + 2) * kstep;
;             const char* a3 = a2 + kstep; const char* b3 = b2 + kstep;
;             PG8_LDB(B0, 0, 0); PG8_LDB(B1, 0, 1); PG8_SCHED; PG8_LDA(At, 0, 0); PG8_STAGE(PG8_SA(1, 1), a1 + hstepA, voffA);
;             PG8_WAIT_V(8); PG8_WAIT_L(0); PG8_BAR; PG8_MMA(0, 0, At, B0); PG8_MMA(0, 1, At, B1); PG8_BAR; PG8_SCHED;
;             PG8_LDA(At, 0, 1); PG8_STAGE(PG8_SB(0, 0), b2, voffB); PG8_STAGE(PG8_SB(0, 1), b2 + hstep, voffB); PG8_STAGE(PG8_SA(0, 0), a2, voffA);
;             PG8_WAIT_V(8); PG8_WAIT_L(0); PG8_BAR; PG8_MMA(1, 0, At, B0); PG8_MMA(1, 1, At, B1); PG8_BAR; PG8_SCHED;
;             PG8_LDB(B0, 1, 0); PG8_LDB(B1, 1, 1); PG8_SCHED; PG8_LDA(At, 1, 0); PG8_STAGE(PG8_SA(0, 1), a2 + hstepA, voffA);
;             PG8_WAIT_V(8); PG8_WAIT_L(0); PG8_BAR; PG8_MMA(0, 0, At, B0); PG8_MMA(0, 1, At, B1); PG8_BAR; PG8_SCHED;
;             PG8_LDA(At, 1, 1); PG8_STAGE(PG8_SB(1, 0), b3, voffB); PG8_STAGE(PG8_SB(1, 1), b3 + hstep, voffB); PG8_STAGE(PG8_SA(1, 0), a3, voffA);
;             PG8_WAIT_V(8); PG8_WAIT_L(0); PG8_BAR; PG8_MMA(1, 0, At, B0); PG8_MMA(1, 1, At, B1); PG8_BAR; PG8_SCHED;
;         }
;         if (ALIGN_EPI) { if (wr == 0) PG8_BAR; }
	s_add_i32 s4, s24, s13
	v_lshl_add_u64 v[168:169], v[168:169], 0, s[30:31]
	s_mov_b32 m0, s4
	ds_read_b128 v[190:193], v188 offset:49152
	ds_read_b128 v[194:197], v188 offset:50176
	ds_read_b128 v[198:201], v188 offset:51200
	ds_read_b128 v[202:205], v188 offset:52224
	ds_read_b128 v[206:209], v188 offset:53248
	ds_read_b128 v[230:233], v188 offset:54272
	ds_read_b128 v[234:237], v188 offset:55296
	ds_read_b128 v[238:241], v188 offset:56320
	global_load_lds_dwordx4 v[168:169], off
	s_add_i32 m0, s4, 0x2000
	s_add_u32 s4, s50, 0xc0080
	v_lshl_add_u64 v[168:169], v[184:185], 0, s[30:31]
	s_addc_u32 s5, s51, 0
	s_add_i32 s24, s25, s13
	global_load_lds_dwordx4 v[168:169], off
	v_lshl_add_u64 v[168:169], s[4:5], 0, v[0:1]
	s_mov_b32 m0, s24
	s_nop 0
	global_load_lds_dwordx4 v[168:169], off
	v_lshl_add_u64 v[168:169], s[4:5], 0, v[154:155]
	s_add_i32 m0, s24, 0x2000
	s_nop 0
	global_load_lds_dwordx4 v[168:169], off
	v_lshl_add_u64 v[168:169], v[214:215], 0, s[30:31]
	s_mov_b32 m0, s36
	s_nop 0
	global_load_lds_dwordx4 v[168:169], off
	v_lshl_add_u64 v[168:169], v[228:229], 0, s[30:31]
	s_mov_b32 m0, s54
	s_nop 0
	global_load_lds_dwordx4 v[168:169], off
	s_waitcnt vmcnt(8)
	s_waitcnt lgkmcnt(0)
	s_barrier
	s_setprio 1
	s_waitcnt lgkmcnt(0)
	v_mfma_f32_16x16x32_bf16 v[62:65], v[130:133], v[190:193], v[62:65]
	v_mfma_f32_16x16x32_bf16 v[58:61], v[138:141], v[190:193], v[58:61]
	v_mfma_f32_16x16x32_bf16 v[50:53], v[130:133], v[198:201], v[50:53]
	v_mfma_f32_16x16x32_bf16 v[42:45], v[138:141], v[198:201], v[42:45]
	v_mfma_f32_16x16x32_bf16 v[34:37], v[130:133], v[206:209], v[34:37]
	v_mfma_f32_16x16x32_bf16 v[26:29], v[138:141], v[206:209], v[26:29]
	v_mfma_f32_16x16x32_bf16 v[18:21], v[130:133], v[234:237], v[18:21]
	v_mfma_f32_16x16x32_bf16 v[10:13], v[138:141], v[234:237], v[10:13]
	v_mfma_f32_16x16x32_bf16 v[62:65], v[134:137], v[194:197], v[62:65]
	v_mfma_f32_16x16x32_bf16 v[58:61], v[142:145], v[194:197], v[58:61]
	v_mfma_f32_16x16x32_bf16 v[50:53], v[134:137], v[202:205], v[50:53]
	v_mfma_f32_16x16x32_bf16 v[42:45], v[142:145], v[202:205], v[42:45]
	v_mfma_f32_16x16x32_bf16 v[34:37], v[134:137], v[230:233], v[34:37]
	v_mfma_f32_16x16x32_bf16 v[26:29], v[142:145], v[230:233], v[26:29]
	v_mfma_f32_16x16x32_bf16 v[18:21], v[134:137], v[238:241], v[18:21]
	v_mfma_f32_16x16x32_bf16 v[10:13], v[142:145], v[238:241], v[10:13]
	s_setprio 0
	s_setprio 1
	v_mfma_f32_16x16x32_bf16 v[54:57], v[146:149], v[190:193], v[54:57]
	v_mfma_f32_16x16x32_bf16 v[46:49], v[164:167], v[190:193], v[46:49]
	v_mfma_f32_16x16x32_bf16 v[38:41], v[146:149], v[198:201], v[38:41]
	v_mfma_f32_16x16x32_bf16 v[30:33], v[164:167], v[198:201], v[30:33]
	v_mfma_f32_16x16x32_bf16 v[22:25], v[146:149], v[206:209], v[22:25]
	v_mfma_f32_16x16x32_bf16 v[14:17], v[164:167], v[206:209], v[14:17]
	v_mfma_f32_16x16x32_bf16 v[6:9], v[146:149], v[234:237], v[6:9]
	v_mfma_f32_16x16x32_bf16 v[2:5], v[164:167], v[234:237], v[2:5]
	v_mfma_f32_16x16x32_bf16 v[54:57], v[150:153], v[194:197], v[54:57]
	v_mfma_f32_16x16x32_bf16 v[46:49], v[180:183], v[194:197], v[46:49]
	v_mfma_f32_16x16x32_bf16 v[38:41], v[150:153], v[202:205], v[38:41]
	v_mfma_f32_16x16x32_bf16 v[30:33], v[180:183], v[202:205], v[30:33]
	v_mfma_f32_16x16x32_bf16 v[22:25], v[150:153], v[230:233], v[22:25]
	v_mfma_f32_16x16x32_bf16 v[14:17], v[180:183], v[230:233], v[14:17]
	v_mfma_f32_16x16x32_bf16 v[6:9], v[150:153], v[238:241], v[6:9]
	v_mfma_f32_16x16x32_bf16 v[2:5], v[180:183], v[238:241], v[2:5]
	s_setprio 0
	s_add_i32 s80, s80, 2
	s_add_u32 s78, s78, 0x100
	s_addc_u32 s79, s79, 0
	s_cmp_gt_u32 s80, 45
	s_mov_b64 s[4:5], s[6:7]
	s_cbranch_scc1 .Lkx_488
	s_add_u32 s6, s4, 0x100
	s_addc_u32 s7, s5, 0
	s_add_i32 s24, 0, 0x10000
	s_cmp_eq_u32 s80, 44
	s_cselect_b32 s53, s43, s7
	s_cselect_b32 s52, s42, s6
	s_cselect_b32 s51, s49, s79
	s_cselect_b32 s50, s48, s78
	s_add_i32 s25, 0, 0x14000
	v_add_u32_e32 v142, s24, v186
	v_add_u32_e32 v168, s25, v186
	s_barrier
	s_branch .Lkr_488
.Lkx_488:
	s_barrier
	s_and_b64 vcc, exec, s[46:47]
	s_cbranch_vccz .LBB0_491
	s_barrier
